# QC full stack with per-block early-barrier tails: 6 MFMAs after the ai=0 block, 2 after the ai=1 block
# speedup vs baseline: 1.0074x; 1.0013x over previous
.LBB0_115:
	ds_read_b128 v[148:151], v154
	ds_read_b128 v[158:161], v154 offset:1024
	ds_read_b128 v[162:165], v154 offset:2048
	ds_read_b128 v[166:169], v154 offset:3072
	ds_read_b128 v[170:173], v155
	ds_read_b128 v[174:177], v155 offset:1024
	ds_read_b128 v[178:181], v155 offset:2048
	ds_read_b128 v[182:185], v155 offset:3072
	s_add_u32 s46, s44, 0xfff00080
	s_addc_u32 s47, s45, -1
	s_cmp_eq_u32 s69, 60
	s_cselect_b32 s49, s35, s47
	s_cselect_b32 s48, s43, s46
	s_cselect_b32 s47, s37, s68
	s_cselect_b32 s46, s66, s67
	v_lshl_add_u64 v[218:219], s[44:45], 0, v[140:141]
	s_add_i32 m0, s54, 0xc000
	ds_read_b128 v[186:189], v156
	ds_read_b128 v[190:193], v156 offset:1024
	ds_read_b128 v[194:197], v156 offset:2048
	ds_read_b128 v[198:201], v156 offset:3072
	ds_read_b128 v[202:205], v156 offset:4096
	ds_read_b128 v[206:209], v156 offset:5120
	ds_read_b128 v[210:213], v156 offset:6144
	ds_read_b128 v[214:217], v156 offset:7168
	global_load_lds_dwordx4 v[218:219], off
	v_lshl_add_u64 v[218:219], s[44:45], 0, v[142:143]
	s_add_i32 m0, s54, 0xe000
	s_nop 0
	global_load_lds_dwordx4 v[218:219], off
	s_waitcnt vmcnt(8)
	s_waitcnt lgkmcnt(0)
	s_barrier
	s_setprio 1
	s_waitcnt lgkmcnt(0)
	v_mfma_f32_16x16x32_bf16 v[126:129], v[148:151], v[186:189], v[126:129]
	v_mfma_f32_16x16x32_bf16 v[122:125], v[162:165], v[186:189], v[122:125]
	v_mfma_f32_16x16x32_bf16 v[118:121], v[148:151], v[194:197], v[118:121]
	v_mfma_f32_16x16x32_bf16 v[110:113], v[162:165], v[194:197], v[110:113]
	v_mfma_f32_16x16x32_bf16 v[102:105], v[148:151], v[202:205], v[102:105]
	v_mfma_f32_16x16x32_bf16 v[94:97], v[162:165], v[202:205], v[94:97]
	v_mfma_f32_16x16x32_bf16 v[86:89], v[148:151], v[210:213], v[86:89]
	v_mfma_f32_16x16x32_bf16 v[78:81], v[162:165], v[210:213], v[78:81]
	v_mfma_f32_16x16x32_bf16 v[126:129], v[158:161], v[190:193], v[126:129]
	v_mfma_f32_16x16x32_bf16 v[122:125], v[166:169], v[190:193], v[122:125]
	v_mfma_f32_16x16x32_bf16 v[118:121], v[158:161], v[198:201], v[118:121]
	v_mfma_f32_16x16x32_bf16 v[110:113], v[166:169], v[198:201], v[110:113]
	v_mfma_f32_16x16x32_bf16 v[102:105], v[158:161], v[206:209], v[102:105]
	v_mfma_f32_16x16x32_bf16 v[94:97], v[166:169], v[206:209], v[94:97]
	v_mfma_f32_16x16x32_bf16 v[86:89], v[158:161], v[214:217], v[86:89]
	v_mfma_f32_16x16x32_bf16 v[78:81], v[166:169], v[214:217], v[78:81]
	s_setprio 0
	s_setprio 1
	v_mfma_f32_16x16x32_bf16 v[114:117], v[170:173], v[186:189], v[114:117]
	v_mfma_f32_16x16x32_bf16 v[106:109], v[178:181], v[186:189], v[106:109]
	v_mfma_f32_16x16x32_bf16 v[98:101], v[170:173], v[194:197], v[98:101]
	v_mfma_f32_16x16x32_bf16 v[90:93], v[178:181], v[194:197], v[90:93]
	v_mfma_f32_16x16x32_bf16 v[82:85], v[170:173], v[202:205], v[82:85]
	v_mfma_f32_16x16x32_bf16 v[74:77], v[178:181], v[202:205], v[74:77]
	v_mfma_f32_16x16x32_bf16 v[70:73], v[170:173], v[210:213], v[70:73]
	v_mfma_f32_16x16x32_bf16 v[66:69], v[178:181], v[210:213], v[66:69]
	v_mfma_f32_16x16x32_bf16 v[114:117], v[174:177], v[190:193], v[114:117]
	v_mfma_f32_16x16x32_bf16 v[106:109], v[182:185], v[190:193], v[106:109]
	s_setprio 3
	s_barrier
	v_mfma_f32_16x16x32_bf16 v[98:101], v[174:177], v[198:201], v[98:101]
	v_mfma_f32_16x16x32_bf16 v[90:93], v[182:185], v[198:201], v[90:93]
	v_mfma_f32_16x16x32_bf16 v[82:85], v[174:177], v[206:209], v[82:85]
	v_mfma_f32_16x16x32_bf16 v[74:77], v[182:185], v[206:209], v[74:77]
	v_mfma_f32_16x16x32_bf16 v[70:73], v[174:177], v[214:217], v[70:73]
	v_mfma_f32_16x16x32_bf16 v[66:69], v[182:185], v[214:217], v[66:69]
	s_setprio 0
	s_add_i32 s70, s64, s51
	v_lshl_add_u64 v[218:219], s[46:47], 0, v[134:135]
	s_mov_b32 m0, s70
	ds_read_b128 v[186:189], v156 offset:16384
	ds_read_b128 v[190:193], v156 offset:17408
	ds_read_b128 v[194:197], v156 offset:18432
	ds_read_b128 v[198:201], v156 offset:19456
	ds_read_b128 v[202:205], v156 offset:20480
	ds_read_b128 v[206:209], v156 offset:21504
	ds_read_b128 v[210:213], v156 offset:22528
	ds_read_b128 v[214:217], v156 offset:23552
	global_load_lds_dwordx4 v[218:219], off
	s_add_i32 m0, s70, 0x2000
	s_add_u32 s70, s46, 0x100000
	v_lshl_add_u64 v[220:221], s[46:47], 0, v[130:131]
	s_addc_u32 s71, s47, 0
	s_add_i32 s72, s65, s51
	global_load_lds_dwordx4 v[220:221], off
	v_lshl_add_u64 v[222:223], s[70:71], 0, v[134:135]
	s_mov_b32 m0, s72
	v_lshl_add_u64 v[224:225], s[48:49], 0, v[132:133]
	global_load_lds_dwordx4 v[222:223], off
	v_lshl_add_u64 v[222:223], s[70:71], 0, v[130:131]
	s_add_i32 m0, s72, 0x2000
	s_nop 0
	global_load_lds_dwordx4 v[222:223], off
	v_lshl_add_u64 v[222:223], s[48:49], 0, v[136:137]
	s_mov_b32 m0, s54
	s_nop 0
	global_load_lds_dwordx4 v[222:223], off
	s_mov_b32 m0, s55
	s_nop 0
	global_load_lds_dwordx4 v[224:225], off
	s_waitcnt vmcnt(8)
	s_waitcnt lgkmcnt(0)
	s_barrier
	s_setprio 1
	s_waitcnt lgkmcnt(0)
	v_mfma_f32_16x16x32_bf16 v[62:65], v[148:151], v[186:189], v[62:65]
	v_mfma_f32_16x16x32_bf16 v[58:61], v[162:165], v[186:189], v[58:61]
	v_mfma_f32_16x16x32_bf16 v[54:57], v[148:151], v[194:197], v[54:57]
	v_mfma_f32_16x16x32_bf16 v[46:49], v[162:165], v[194:197], v[46:49]
	v_mfma_f32_16x16x32_bf16 v[38:41], v[148:151], v[202:205], v[38:41]
	v_mfma_f32_16x16x32_bf16 v[30:33], v[162:165], v[202:205], v[30:33]
	v_mfma_f32_16x16x32_bf16 v[22:25], v[148:151], v[210:213], v[22:25]
	v_mfma_f32_16x16x32_bf16 v[14:17], v[162:165], v[210:213], v[14:17]
	v_mfma_f32_16x16x32_bf16 v[62:65], v[158:161], v[190:193], v[62:65]
	v_mfma_f32_16x16x32_bf16 v[58:61], v[166:169], v[190:193], v[58:61]
	v_mfma_f32_16x16x32_bf16 v[54:57], v[158:161], v[198:201], v[54:57]
	v_mfma_f32_16x16x32_bf16 v[46:49], v[166:169], v[198:201], v[46:49]
	v_mfma_f32_16x16x32_bf16 v[38:41], v[158:161], v[206:209], v[38:41]
	v_mfma_f32_16x16x32_bf16 v[30:33], v[166:169], v[206:209], v[30:33]
	v_mfma_f32_16x16x32_bf16 v[22:25], v[158:161], v[214:217], v[22:25]
	v_mfma_f32_16x16x32_bf16 v[14:17], v[166:169], v[214:217], v[14:17]
	s_setprio 0
	s_setprio 1
	v_mfma_f32_16x16x32_bf16 v[50:53], v[170:173], v[186:189], v[50:53]
	v_mfma_f32_16x16x32_bf16 v[42:45], v[178:181], v[186:189], v[42:45]
	v_mfma_f32_16x16x32_bf16 v[34:37], v[170:173], v[194:197], v[34:37]
	v_mfma_f32_16x16x32_bf16 v[26:29], v[178:181], v[194:197], v[26:29]
	v_mfma_f32_16x16x32_bf16 v[18:21], v[170:173], v[202:205], v[18:21]
	v_mfma_f32_16x16x32_bf16 v[10:13], v[178:181], v[202:205], v[10:13]
	v_mfma_f32_16x16x32_bf16 v[6:9], v[170:173], v[210:213], v[6:9]
	v_mfma_f32_16x16x32_bf16 v[2:5], v[178:181], v[210:213], v[2:5]
	v_mfma_f32_16x16x32_bf16 v[50:53], v[174:177], v[190:193], v[50:53]
	v_mfma_f32_16x16x32_bf16 v[42:45], v[182:185], v[190:193], v[42:45]
	v_mfma_f32_16x16x32_bf16 v[34:37], v[174:177], v[198:201], v[34:37]
	v_mfma_f32_16x16x32_bf16 v[26:29], v[182:185], v[198:201], v[26:29]
	v_mfma_f32_16x16x32_bf16 v[18:21], v[174:177], v[206:209], v[18:21]
	v_mfma_f32_16x16x32_bf16 v[10:13], v[182:185], v[206:209], v[10:13]
	s_setprio 3
	s_barrier
	v_mfma_f32_16x16x32_bf16 v[6:9], v[174:177], v[214:217], v[6:9]
	v_mfma_f32_16x16x32_bf16 v[2:5], v[182:185], v[214:217], v[2:5]
	s_setprio 0
	s_add_i32 s70, 0, 0x18000
	v_add_u32_e32 v138, s70, v152
	s_add_i32 s71, 0, 0x1c000
	ds_read_b128 v[148:151], v138
	ds_read_b128 v[158:161], v138 offset:1024
	ds_read_b128 v[162:165], v138 offset:2048
	ds_read_b128 v[166:169], v138 offset:3072
	v_add_u32_e32 v138, s71, v152
	ds_read_b128 v[170:173], v138
	ds_read_b128 v[174:177], v138 offset:1024
	ds_read_b128 v[178:181], v138 offset:2048
	ds_read_b128 v[182:185], v138 offset:3072
	s_add_u32 s48, s48, 0x100000
	s_addc_u32 s49, s49, 0
	s_mov_b32 m0, s56
	v_lshl_add_u64 v[226:227], s[48:49], 0, v[136:137]
	ds_read_b128 v[186:189], v156 offset:32768
	ds_read_b128 v[190:193], v156 offset:33792
	ds_read_b128 v[194:197], v156 offset:34816
	ds_read_b128 v[198:201], v156 offset:35840
	ds_read_b128 v[202:205], v156 offset:36864
	ds_read_b128 v[206:209], v156 offset:37888
	ds_read_b128 v[210:213], v156 offset:38912
	ds_read_b128 v[214:217], v156 offset:39936
	global_load_lds_dwordx4 v[226:227], off
	v_lshl_add_u64 v[226:227], s[48:49], 0, v[132:133]
	s_mov_b32 m0, s57
	s_nop 0
	global_load_lds_dwordx4 v[226:227], off
	s_waitcnt vmcnt(8)
	s_waitcnt lgkmcnt(0)
	s_barrier
	s_setprio 1
	s_waitcnt lgkmcnt(0)
	v_mfma_f32_16x16x32_bf16 v[126:129], v[148:151], v[186:189], v[126:129]
	v_mfma_f32_16x16x32_bf16 v[122:125], v[162:165], v[186:189], v[122:125]
	v_mfma_f32_16x16x32_bf16 v[118:121], v[148:151], v[194:197], v[118:121]
	v_mfma_f32_16x16x32_bf16 v[110:113], v[162:165], v[194:197], v[110:113]
	v_mfma_f32_16x16x32_bf16 v[102:105], v[148:151], v[202:205], v[102:105]
	v_mfma_f32_16x16x32_bf16 v[94:97], v[162:165], v[202:205], v[94:97]
	v_mfma_f32_16x16x32_bf16 v[86:89], v[148:151], v[210:213], v[86:89]
	v_mfma_f32_16x16x32_bf16 v[78:81], v[162:165], v[210:213], v[78:81]
	v_mfma_f32_16x16x32_bf16 v[126:129], v[158:161], v[190:193], v[126:129]
	v_mfma_f32_16x16x32_bf16 v[122:125], v[166:169], v[190:193], v[122:125]
	v_mfma_f32_16x16x32_bf16 v[118:121], v[158:161], v[198:201], v[118:121]
	v_mfma_f32_16x16x32_bf16 v[110:113], v[166:169], v[198:201], v[110:113]
	v_mfma_f32_16x16x32_bf16 v[102:105], v[158:161], v[206:209], v[102:105]
	v_mfma_f32_16x16x32_bf16 v[94:97], v[166:169], v[206:209], v[94:97]
	v_mfma_f32_16x16x32_bf16 v[86:89], v[158:161], v[214:217], v[86:89]
	v_mfma_f32_16x16x32_bf16 v[78:81], v[166:169], v[214:217], v[78:81]
	s_setprio 0
	s_setprio 1
	v_mfma_f32_16x16x32_bf16 v[114:117], v[170:173], v[186:189], v[114:117]
	v_mfma_f32_16x16x32_bf16 v[106:109], v[178:181], v[186:189], v[106:109]
	v_mfma_f32_16x16x32_bf16 v[98:101], v[170:173], v[194:197], v[98:101]
	v_mfma_f32_16x16x32_bf16 v[90:93], v[178:181], v[194:197], v[90:93]
	v_mfma_f32_16x16x32_bf16 v[82:85], v[170:173], v[202:205], v[82:85]
	v_mfma_f32_16x16x32_bf16 v[74:77], v[178:181], v[202:205], v[74:77]
	v_mfma_f32_16x16x32_bf16 v[70:73], v[170:173], v[210:213], v[70:73]
	v_mfma_f32_16x16x32_bf16 v[66:69], v[178:181], v[210:213], v[66:69]
	v_mfma_f32_16x16x32_bf16 v[114:117], v[174:177], v[190:193], v[114:117]
	v_mfma_f32_16x16x32_bf16 v[106:109], v[182:185], v[190:193], v[106:109]
	s_setprio 3
	s_barrier
	v_mfma_f32_16x16x32_bf16 v[98:101], v[174:177], v[198:201], v[98:101]
	v_mfma_f32_16x16x32_bf16 v[90:93], v[182:185], v[198:201], v[90:93]
	v_mfma_f32_16x16x32_bf16 v[82:85], v[174:177], v[206:209], v[82:85]
	v_mfma_f32_16x16x32_bf16 v[74:77], v[182:185], v[206:209], v[74:77]
	v_mfma_f32_16x16x32_bf16 v[70:73], v[174:177], v[214:217], v[70:73]
	v_mfma_f32_16x16x32_bf16 v[66:69], v[182:185], v[214:217], v[66:69]
	s_setprio 0
	s_add_i32 s48, s70, s51
	v_lshl_add_u64 v[218:219], v[218:219], 0, s[28:29]
	s_mov_b32 m0, s48
	ds_read_b128 v[186:189], v156 offset:49152
	ds_read_b128 v[190:193], v156 offset:50176
	ds_read_b128 v[194:197], v156 offset:51200
	ds_read_b128 v[198:201], v156 offset:52224
	ds_read_b128 v[202:205], v156 offset:53248
	ds_read_b128 v[206:209], v156 offset:54272
	ds_read_b128 v[210:213], v156 offset:55296
	ds_read_b128 v[214:217], v156 offset:56320
	global_load_lds_dwordx4 v[218:219], off
	s_add_i32 m0, s48, 0x2000
	s_add_u32 s46, s46, 0x100080
	v_lshl_add_u64 v[218:219], v[220:221], 0, s[28:29]
	s_addc_u32 s47, s47, 0
	s_add_i32 s48, s71, s51
	global_load_lds_dwordx4 v[218:219], off
	v_lshl_add_u64 v[218:219], s[46:47], 0, v[134:135]
	s_mov_b32 m0, s48
	s_nop 0
	global_load_lds_dwordx4 v[218:219], off
	v_lshl_add_u64 v[218:219], s[46:47], 0, v[130:131]
	s_add_i32 m0, s48, 0x2000
	s_nop 0
	global_load_lds_dwordx4 v[218:219], off
	v_lshl_add_u64 v[218:219], v[222:223], 0, s[28:29]
	s_mov_b32 m0, s59
	s_nop 0
	global_load_lds_dwordx4 v[218:219], off
	v_lshl_add_u64 v[218:219], v[224:225], 0, s[28:29]
	s_mov_b32 m0, s60
	s_nop 0
	global_load_lds_dwordx4 v[218:219], off
	s_waitcnt vmcnt(8)
	s_waitcnt lgkmcnt(0)
	s_barrier
	s_setprio 1
	s_waitcnt lgkmcnt(0)
	v_mfma_f32_16x16x32_bf16 v[62:65], v[148:151], v[186:189], v[62:65]
	v_mfma_f32_16x16x32_bf16 v[58:61], v[162:165], v[186:189], v[58:61]
	v_mfma_f32_16x16x32_bf16 v[54:57], v[148:151], v[194:197], v[54:57]
	v_mfma_f32_16x16x32_bf16 v[46:49], v[162:165], v[194:197], v[46:49]
	v_mfma_f32_16x16x32_bf16 v[38:41], v[148:151], v[202:205], v[38:41]
	v_mfma_f32_16x16x32_bf16 v[30:33], v[162:165], v[202:205], v[30:33]
	v_mfma_f32_16x16x32_bf16 v[22:25], v[148:151], v[210:213], v[22:25]
	v_mfma_f32_16x16x32_bf16 v[14:17], v[162:165], v[210:213], v[14:17]
	v_mfma_f32_16x16x32_bf16 v[62:65], v[158:161], v[190:193], v[62:65]
	v_mfma_f32_16x16x32_bf16 v[58:61], v[166:169], v[190:193], v[58:61]
	v_mfma_f32_16x16x32_bf16 v[54:57], v[158:161], v[198:201], v[54:57]
	v_mfma_f32_16x16x32_bf16 v[46:49], v[166:169], v[198:201], v[46:49]
	v_mfma_f32_16x16x32_bf16 v[38:41], v[158:161], v[206:209], v[38:41]
	v_mfma_f32_16x16x32_bf16 v[30:33], v[166:169], v[206:209], v[30:33]
	v_mfma_f32_16x16x32_bf16 v[22:25], v[158:161], v[214:217], v[22:25]
	v_mfma_f32_16x16x32_bf16 v[14:17], v[166:169], v[214:217], v[14:17]
	s_setprio 0
	s_setprio 1
	v_mfma_f32_16x16x32_bf16 v[50:53], v[170:173], v[186:189], v[50:53]
	v_mfma_f32_16x16x32_bf16 v[42:45], v[178:181], v[186:189], v[42:45]
	v_mfma_f32_16x16x32_bf16 v[34:37], v[170:173], v[194:197], v[34:37]
	v_mfma_f32_16x16x32_bf16 v[26:29], v[178:181], v[194:197], v[26:29]
	v_mfma_f32_16x16x32_bf16 v[18:21], v[170:173], v[202:205], v[18:21]
	v_mfma_f32_16x16x32_bf16 v[10:13], v[178:181], v[202:205], v[10:13]
	v_mfma_f32_16x16x32_bf16 v[6:9], v[170:173], v[210:213], v[6:9]
	v_mfma_f32_16x16x32_bf16 v[2:5], v[178:181], v[210:213], v[2:5]
	v_mfma_f32_16x16x32_bf16 v[50:53], v[174:177], v[190:193], v[50:53]
	v_mfma_f32_16x16x32_bf16 v[42:45], v[182:185], v[190:193], v[42:45]
	v_mfma_f32_16x16x32_bf16 v[34:37], v[174:177], v[198:201], v[34:37]
	v_mfma_f32_16x16x32_bf16 v[26:29], v[182:185], v[198:201], v[26:29]
	v_mfma_f32_16x16x32_bf16 v[18:21], v[174:177], v[206:209], v[18:21]
	v_mfma_f32_16x16x32_bf16 v[10:13], v[182:185], v[206:209], v[10:13]
	s_setprio 3
	s_barrier
	v_mfma_f32_16x16x32_bf16 v[6:9], v[174:177], v[214:217], v[6:9]
	v_mfma_f32_16x16x32_bf16 v[2:5], v[182:185], v[214:217], v[2:5]
	s_setprio 0
	s_add_i32 s69, s69, 2
	s_add_u32 s44, s44, 0x100
	s_addc_u32 s45, s45, 0
	s_add_u32 s67, s67, 0x100
	s_addc_u32 s68, s68, 0
	s_cmp_gt_u32 s69, 61
	s_cbranch_scc0 .LBB0_115
	s_and_b64 vcc, exec, s[30:31]
	s_cbranch_vccz .LBB0_118
	s_barrier

.LBB0_540:
	v_add_u32_e32 v139, s64, v186
	ds_read_b128 v[130:133], v139
	ds_read_b128 v[134:137], v139 offset:1024
	ds_read_b128 v[146:149], v139 offset:2048
	ds_read_b128 v[150:153], v139 offset:3072
	v_add_u32_e32 v139, s65, v186
	s_add_u32 s48, s44, s46
	ds_read_b128 v[154:157], v139
	ds_read_b128 v[174:177], v139 offset:1024
	ds_read_b128 v[178:181], v139 offset:2048
	ds_read_b128 v[182:185], v139 offset:3072
	s_addc_u32 s49, s45, s47
	s_add_u32 s48, s48, 0x100
	s_addc_u32 s49, s49, 0
	s_add_u32 s71, s68, s46
	s_addc_u32 s72, s69, s47
	s_cmpk_eq_i32 s46, 0x1f00
	s_cselect_b32 s51, s39, s49
	s_cselect_b32 s50, s66, s48
	s_cselect_b32 s49, s37, s72
	s_cselect_b32 s48, s67, s71
	v_lshl_add_u64 v[222:223], v[142:143], 0, s[46:47]
	s_add_i32 m0, s55, 0xc000
	ds_read_b128 v[190:193], v188
	ds_read_b128 v[194:197], v188 offset:1024
	ds_read_b128 v[198:201], v188 offset:2048
	ds_read_b128 v[202:205], v188 offset:3072
	ds_read_b128 v[206:209], v188 offset:4096
	ds_read_b128 v[210:213], v188 offset:5120
	ds_read_b128 v[214:217], v188 offset:6144
	ds_read_b128 v[218:221], v188 offset:7168
	global_load_lds_dwordx4 v[222:223], off
	v_lshl_add_u64 v[222:223], v[144:145], 0, s[46:47]
	s_add_i32 m0, s55, 0xe000
	s_nop 0
	global_load_lds_dwordx4 v[222:223], off
	s_waitcnt vmcnt(8)
	s_waitcnt lgkmcnt(0)
	s_barrier
	s_setprio 1
	s_waitcnt lgkmcnt(0)
	v_mfma_f32_16x16x32_bf16 v[126:129], v[130:133], v[190:193], v[126:129]
	v_mfma_f32_16x16x32_bf16 v[122:125], v[146:149], v[190:193], v[122:125]
	v_mfma_f32_16x16x32_bf16 v[114:117], v[130:133], v[198:201], v[114:117]
	v_mfma_f32_16x16x32_bf16 v[106:109], v[146:149], v[198:201], v[106:109]
	v_mfma_f32_16x16x32_bf16 v[98:101], v[130:133], v[206:209], v[98:101]
	v_mfma_f32_16x16x32_bf16 v[90:93], v[146:149], v[206:209], v[90:93]
	v_mfma_f32_16x16x32_bf16 v[82:85], v[130:133], v[214:217], v[82:85]
	v_mfma_f32_16x16x32_bf16 v[74:77], v[146:149], v[214:217], v[74:77]
	v_mfma_f32_16x16x32_bf16 v[126:129], v[134:137], v[194:197], v[126:129]
	v_mfma_f32_16x16x32_bf16 v[122:125], v[150:153], v[194:197], v[122:125]
	v_mfma_f32_16x16x32_bf16 v[114:117], v[134:137], v[202:205], v[114:117]
	v_mfma_f32_16x16x32_bf16 v[106:109], v[150:153], v[202:205], v[106:109]
	v_mfma_f32_16x16x32_bf16 v[98:101], v[134:137], v[210:213], v[98:101]
	v_mfma_f32_16x16x32_bf16 v[90:93], v[150:153], v[210:213], v[90:93]
	v_mfma_f32_16x16x32_bf16 v[82:85], v[134:137], v[218:221], v[82:85]
	v_mfma_f32_16x16x32_bf16 v[74:77], v[150:153], v[218:221], v[74:77]
	s_setprio 0
	s_setprio 1
	v_mfma_f32_16x16x32_bf16 v[118:121], v[154:157], v[190:193], v[118:121]
	v_mfma_f32_16x16x32_bf16 v[110:113], v[178:181], v[190:193], v[110:113]
	v_mfma_f32_16x16x32_bf16 v[102:105], v[154:157], v[198:201], v[102:105]
	v_mfma_f32_16x16x32_bf16 v[94:97], v[178:181], v[198:201], v[94:97]
	v_mfma_f32_16x16x32_bf16 v[86:89], v[154:157], v[206:209], v[86:89]
	v_mfma_f32_16x16x32_bf16 v[78:81], v[178:181], v[206:209], v[78:81]
	v_mfma_f32_16x16x32_bf16 v[70:73], v[154:157], v[214:217], v[70:73]
	v_mfma_f32_16x16x32_bf16 v[66:69], v[178:181], v[214:217], v[66:69]
	v_mfma_f32_16x16x32_bf16 v[118:121], v[174:177], v[194:197], v[118:121]
	v_mfma_f32_16x16x32_bf16 v[110:113], v[182:185], v[194:197], v[110:113]
	s_setprio 3
	s_barrier
	v_mfma_f32_16x16x32_bf16 v[102:105], v[174:177], v[202:205], v[102:105]
	v_mfma_f32_16x16x32_bf16 v[94:97], v[182:185], v[202:205], v[94:97]
	v_mfma_f32_16x16x32_bf16 v[86:89], v[174:177], v[210:213], v[86:89]
	v_mfma_f32_16x16x32_bf16 v[78:81], v[182:185], v[210:213], v[78:81]
	v_mfma_f32_16x16x32_bf16 v[70:73], v[174:177], v[218:221], v[70:73]
	v_mfma_f32_16x16x32_bf16 v[66:69], v[182:185], v[218:221], v[66:69]
	s_setprio 0
	s_add_i32 s71, s64, s54
	v_lshl_add_u64 v[222:223], s[48:49], 0, v[160:161]
	s_mov_b32 m0, s71
	ds_read_b128 v[190:193], v188 offset:16384
	ds_read_b128 v[194:197], v188 offset:17408
	ds_read_b128 v[198:201], v188 offset:18432
	ds_read_b128 v[202:205], v188 offset:19456
	ds_read_b128 v[206:209], v188 offset:20480
	ds_read_b128 v[210:213], v188 offset:21504
	ds_read_b128 v[214:217], v188 offset:22528
	ds_read_b128 v[218:221], v188 offset:23552
	global_load_lds_dwordx4 v[222:223], off
	s_add_i32 m0, s71, 0x2000
	s_add_u32 s72, s48, 0x100000
	v_lshl_add_u64 v[224:225], s[48:49], 0, v[164:165]
	s_addc_u32 s73, s49, 0
	s_add_i32 s71, s65, s54
	global_load_lds_dwordx4 v[224:225], off
	v_lshl_add_u64 v[226:227], s[72:73], 0, v[160:161]
	s_mov_b32 m0, s71
	v_lshl_add_u64 v[228:229], s[50:51], 0, v[162:163]
	global_load_lds_dwordx4 v[226:227], off
	v_lshl_add_u64 v[226:227], s[72:73], 0, v[164:165]
	s_add_i32 m0, s71, 0x2000
	s_nop 0
	global_load_lds_dwordx4 v[226:227], off
	v_lshl_add_u64 v[226:227], s[50:51], 0, v[158:159]
	s_mov_b32 m0, s55
	s_nop 0
	global_load_lds_dwordx4 v[226:227], off
	s_mov_b32 m0, s56
	s_nop 0
	global_load_lds_dwordx4 v[228:229], off
	s_waitcnt vmcnt(8)
	s_waitcnt lgkmcnt(0)
	s_barrier
	s_setprio 1
	s_waitcnt lgkmcnt(0)
	v_mfma_f32_16x16x32_bf16 v[62:65], v[130:133], v[190:193], v[62:65]
	v_mfma_f32_16x16x32_bf16 v[58:61], v[146:149], v[190:193], v[58:61]
	v_mfma_f32_16x16x32_bf16 v[50:53], v[130:133], v[198:201], v[50:53]
	v_mfma_f32_16x16x32_bf16 v[42:45], v[146:149], v[198:201], v[42:45]
	v_mfma_f32_16x16x32_bf16 v[34:37], v[130:133], v[206:209], v[34:37]
	v_mfma_f32_16x16x32_bf16 v[26:29], v[146:149], v[206:209], v[26:29]
	v_mfma_f32_16x16x32_bf16 v[18:21], v[130:133], v[214:217], v[18:21]
	v_mfma_f32_16x16x32_bf16 v[10:13], v[146:149], v[214:217], v[10:13]
	v_mfma_f32_16x16x32_bf16 v[62:65], v[134:137], v[194:197], v[62:65]
	v_mfma_f32_16x16x32_bf16 v[58:61], v[150:153], v[194:197], v[58:61]
	v_mfma_f32_16x16x32_bf16 v[50:53], v[134:137], v[202:205], v[50:53]
	v_mfma_f32_16x16x32_bf16 v[42:45], v[150:153], v[202:205], v[42:45]
	v_mfma_f32_16x16x32_bf16 v[34:37], v[134:137], v[210:213], v[34:37]
	v_mfma_f32_16x16x32_bf16 v[26:29], v[150:153], v[210:213], v[26:29]
	v_mfma_f32_16x16x32_bf16 v[18:21], v[134:137], v[218:221], v[18:21]
	v_mfma_f32_16x16x32_bf16 v[10:13], v[150:153], v[218:221], v[10:13]
	s_setprio 0
	s_setprio 1
	v_mfma_f32_16x16x32_bf16 v[54:57], v[154:157], v[190:193], v[54:57]
	v_mfma_f32_16x16x32_bf16 v[46:49], v[178:181], v[190:193], v[46:49]
	v_mfma_f32_16x16x32_bf16 v[38:41], v[154:157], v[198:201], v[38:41]
	v_mfma_f32_16x16x32_bf16 v[30:33], v[178:181], v[198:201], v[30:33]
	v_mfma_f32_16x16x32_bf16 v[22:25], v[154:157], v[206:209], v[22:25]
	v_mfma_f32_16x16x32_bf16 v[14:17], v[178:181], v[206:209], v[14:17]
	v_mfma_f32_16x16x32_bf16 v[6:9], v[154:157], v[214:217], v[6:9]
	v_mfma_f32_16x16x32_bf16 v[2:5], v[178:181], v[214:217], v[2:5]
	v_mfma_f32_16x16x32_bf16 v[54:57], v[174:177], v[194:197], v[54:57]
	v_mfma_f32_16x16x32_bf16 v[46:49], v[182:185], v[194:197], v[46:49]
	v_mfma_f32_16x16x32_bf16 v[38:41], v[174:177], v[202:205], v[38:41]
	v_mfma_f32_16x16x32_bf16 v[30:33], v[182:185], v[202:205], v[30:33]
	v_mfma_f32_16x16x32_bf16 v[22:25], v[174:177], v[210:213], v[22:25]
	v_mfma_f32_16x16x32_bf16 v[14:17], v[182:185], v[210:213], v[14:17]
	s_setprio 3
	s_barrier
	v_mfma_f32_16x16x32_bf16 v[6:9], v[174:177], v[218:221], v[6:9]
	v_mfma_f32_16x16x32_bf16 v[2:5], v[182:185], v[218:221], v[2:5]
	s_setprio 0
	s_add_i32 s71, 0, 0x18000
	v_add_u32_e32 v139, s71, v186
	s_add_i32 s72, 0, 0x1c000
	ds_read_b128 v[130:133], v139
	ds_read_b128 v[134:137], v139 offset:1024
	ds_read_b128 v[146:149], v139 offset:2048
	ds_read_b128 v[150:153], v139 offset:3072
	v_add_u32_e32 v139, s72, v186
	ds_read_b128 v[154:157], v139
	ds_read_b128 v[174:177], v139 offset:1024
	ds_read_b128 v[178:181], v139 offset:2048
	ds_read_b128 v[182:185], v139 offset:3072
	s_add_u32 s50, s50, 0x100000
	s_addc_u32 s51, s51, 0
	s_mov_b32 m0, s57
	v_lshl_add_u64 v[230:231], s[50:51], 0, v[158:159]
	ds_read_b128 v[190:193], v188 offset:32768
	ds_read_b128 v[194:197], v188 offset:33792
	ds_read_b128 v[198:201], v188 offset:34816
	ds_read_b128 v[202:205], v188 offset:35840
	ds_read_b128 v[206:209], v188 offset:36864
	ds_read_b128 v[210:213], v188 offset:37888
	ds_read_b128 v[214:217], v188 offset:38912
	ds_read_b128 v[218:221], v188 offset:39936
	global_load_lds_dwordx4 v[230:231], off
	v_lshl_add_u64 v[230:231], s[50:51], 0, v[162:163]
	s_mov_b32 m0, s58
	s_nop 0
	global_load_lds_dwordx4 v[230:231], off
	s_waitcnt vmcnt(8)
	s_waitcnt lgkmcnt(0)
	s_barrier
	s_setprio 1
	s_waitcnt lgkmcnt(0)
	v_mfma_f32_16x16x32_bf16 v[126:129], v[130:133], v[190:193], v[126:129]
	v_mfma_f32_16x16x32_bf16 v[122:125], v[146:149], v[190:193], v[122:125]
	v_mfma_f32_16x16x32_bf16 v[114:117], v[130:133], v[198:201], v[114:117]
	v_mfma_f32_16x16x32_bf16 v[106:109], v[146:149], v[198:201], v[106:109]
	v_mfma_f32_16x16x32_bf16 v[98:101], v[130:133], v[206:209], v[98:101]
	v_mfma_f32_16x16x32_bf16 v[90:93], v[146:149], v[206:209], v[90:93]
	v_mfma_f32_16x16x32_bf16 v[82:85], v[130:133], v[214:217], v[82:85]
	v_mfma_f32_16x16x32_bf16 v[74:77], v[146:149], v[214:217], v[74:77]
	v_mfma_f32_16x16x32_bf16 v[126:129], v[134:137], v[194:197], v[126:129]
	v_mfma_f32_16x16x32_bf16 v[122:125], v[150:153], v[194:197], v[122:125]
	v_mfma_f32_16x16x32_bf16 v[114:117], v[134:137], v[202:205], v[114:117]
	v_mfma_f32_16x16x32_bf16 v[106:109], v[150:153], v[202:205], v[106:109]
	v_mfma_f32_16x16x32_bf16 v[98:101], v[134:137], v[210:213], v[98:101]
	v_mfma_f32_16x16x32_bf16 v[90:93], v[150:153], v[210:213], v[90:93]
	v_mfma_f32_16x16x32_bf16 v[82:85], v[134:137], v[218:221], v[82:85]
	v_mfma_f32_16x16x32_bf16 v[74:77], v[150:153], v[218:221], v[74:77]
	s_setprio 0
	s_setprio 1
	v_mfma_f32_16x16x32_bf16 v[118:121], v[154:157], v[190:193], v[118:121]
	v_mfma_f32_16x16x32_bf16 v[110:113], v[178:181], v[190:193], v[110:113]
	v_mfma_f32_16x16x32_bf16 v[102:105], v[154:157], v[198:201], v[102:105]
	v_mfma_f32_16x16x32_bf16 v[94:97], v[178:181], v[198:201], v[94:97]
	v_mfma_f32_16x16x32_bf16 v[86:89], v[154:157], v[206:209], v[86:89]
	v_mfma_f32_16x16x32_bf16 v[78:81], v[178:181], v[206:209], v[78:81]
	v_mfma_f32_16x16x32_bf16 v[70:73], v[154:157], v[214:217], v[70:73]
	v_mfma_f32_16x16x32_bf16 v[66:69], v[178:181], v[214:217], v[66:69]
	v_mfma_f32_16x16x32_bf16 v[118:121], v[174:177], v[194:197], v[118:121]
	v_mfma_f32_16x16x32_bf16 v[110:113], v[182:185], v[194:197], v[110:113]
	s_setprio 3
	s_barrier
	v_mfma_f32_16x16x32_bf16 v[102:105], v[174:177], v[202:205], v[102:105]
	v_mfma_f32_16x16x32_bf16 v[94:97], v[182:185], v[202:205], v[94:97]
	v_mfma_f32_16x16x32_bf16 v[86:89], v[174:177], v[210:213], v[86:89]
	v_mfma_f32_16x16x32_bf16 v[78:81], v[182:185], v[210:213], v[78:81]
	v_mfma_f32_16x16x32_bf16 v[70:73], v[174:177], v[218:221], v[70:73]
	v_mfma_f32_16x16x32_bf16 v[66:69], v[182:185], v[218:221], v[66:69]
	s_setprio 0
	s_add_i32 s50, s71, s54
	v_lshl_add_u64 v[222:223], v[222:223], 0, s[30:31]
	s_mov_b32 m0, s50
	ds_read_b128 v[190:193], v188 offset:49152
	ds_read_b128 v[194:197], v188 offset:50176
	ds_read_b128 v[198:201], v188 offset:51200
	ds_read_b128 v[202:205], v188 offset:52224
	ds_read_b128 v[206:209], v188 offset:53248
	ds_read_b128 v[210:213], v188 offset:54272
	ds_read_b128 v[214:217], v188 offset:55296
	ds_read_b128 v[218:221], v188 offset:56320
	global_load_lds_dwordx4 v[222:223], off
	s_add_i32 m0, s50, 0x2000
	s_add_u32 s48, s48, 0x100080
	v_lshl_add_u64 v[222:223], v[224:225], 0, s[30:31]
	s_addc_u32 s49, s49, 0
	s_add_i32 s50, s72, s54
	global_load_lds_dwordx4 v[222:223], off
	v_lshl_add_u64 v[222:223], s[48:49], 0, v[160:161]
	s_mov_b32 m0, s50
	s_nop 0
	global_load_lds_dwordx4 v[222:223], off
	v_lshl_add_u64 v[222:223], s[48:49], 0, v[164:165]
	s_add_i32 m0, s50, 0x2000
	s_nop 0
	global_load_lds_dwordx4 v[222:223], off
	v_lshl_add_u64 v[222:223], v[226:227], 0, s[30:31]
	s_mov_b32 m0, s60
	s_nop 0
	global_load_lds_dwordx4 v[222:223], off
	v_lshl_add_u64 v[222:223], v[228:229], 0, s[30:31]
	s_mov_b32 m0, s61
	s_nop 0
	global_load_lds_dwordx4 v[222:223], off
	s_waitcnt vmcnt(8)
	s_waitcnt lgkmcnt(0)
	s_barrier
	s_setprio 1
	s_waitcnt lgkmcnt(0)
	v_mfma_f32_16x16x32_bf16 v[62:65], v[130:133], v[190:193], v[62:65]
	v_mfma_f32_16x16x32_bf16 v[58:61], v[146:149], v[190:193], v[58:61]
	v_mfma_f32_16x16x32_bf16 v[50:53], v[130:133], v[198:201], v[50:53]
	v_mfma_f32_16x16x32_bf16 v[42:45], v[146:149], v[198:201], v[42:45]
	v_mfma_f32_16x16x32_bf16 v[34:37], v[130:133], v[206:209], v[34:37]
	v_mfma_f32_16x16x32_bf16 v[26:29], v[146:149], v[206:209], v[26:29]
	v_mfma_f32_16x16x32_bf16 v[18:21], v[130:133], v[214:217], v[18:21]
	v_mfma_f32_16x16x32_bf16 v[10:13], v[146:149], v[214:217], v[10:13]
	v_mfma_f32_16x16x32_bf16 v[62:65], v[134:137], v[194:197], v[62:65]
	v_mfma_f32_16x16x32_bf16 v[58:61], v[150:153], v[194:197], v[58:61]
	v_mfma_f32_16x16x32_bf16 v[50:53], v[134:137], v[202:205], v[50:53]
	v_mfma_f32_16x16x32_bf16 v[42:45], v[150:153], v[202:205], v[42:45]
	v_mfma_f32_16x16x32_bf16 v[34:37], v[134:137], v[210:213], v[34:37]
	v_mfma_f32_16x16x32_bf16 v[26:29], v[150:153], v[210:213], v[26:29]
	v_mfma_f32_16x16x32_bf16 v[18:21], v[134:137], v[218:221], v[18:21]
	v_mfma_f32_16x16x32_bf16 v[10:13], v[150:153], v[218:221], v[10:13]
	s_setprio 0
	s_setprio 1
	v_mfma_f32_16x16x32_bf16 v[54:57], v[154:157], v[190:193], v[54:57]
	v_mfma_f32_16x16x32_bf16 v[46:49], v[178:181], v[190:193], v[46:49]
	v_mfma_f32_16x16x32_bf16 v[38:41], v[154:157], v[198:201], v[38:41]
	v_mfma_f32_16x16x32_bf16 v[30:33], v[178:181], v[198:201], v[30:33]
	v_mfma_f32_16x16x32_bf16 v[22:25], v[154:157], v[206:209], v[22:25]
	v_mfma_f32_16x16x32_bf16 v[14:17], v[178:181], v[206:209], v[14:17]
	v_mfma_f32_16x16x32_bf16 v[6:9], v[154:157], v[214:217], v[6:9]
	v_mfma_f32_16x16x32_bf16 v[2:5], v[178:181], v[214:217], v[2:5]
	v_mfma_f32_16x16x32_bf16 v[54:57], v[174:177], v[194:197], v[54:57]
	v_mfma_f32_16x16x32_bf16 v[46:49], v[182:185], v[194:197], v[46:49]
	v_mfma_f32_16x16x32_bf16 v[38:41], v[174:177], v[202:205], v[38:41]
	v_mfma_f32_16x16x32_bf16 v[30:33], v[182:185], v[202:205], v[30:33]
	v_mfma_f32_16x16x32_bf16 v[22:25], v[174:177], v[210:213], v[22:25]
	v_mfma_f32_16x16x32_bf16 v[14:17], v[182:185], v[210:213], v[14:17]
	s_setprio 3
	s_barrier
	v_mfma_f32_16x16x32_bf16 v[6:9], v[174:177], v[218:221], v[6:9]
	v_mfma_f32_16x16x32_bf16 v[2:5], v[182:185], v[218:221], v[2:5]
	s_setprio 0
	s_add_i32 s70, s70, 2
	s_add_u32 s46, s46, 0x100
	s_addc_u32 s47, s47, 0
	s_cmp_gt_u32 s70, 61
	s_cbranch_scc1 .LBB0_543

.LBB0_618:
	ds_read_b128 v[146:149], v154
	ds_read_b128 v[158:161], v154 offset:1024
	ds_read_b128 v[162:165], v154 offset:2048
	ds_read_b128 v[166:169], v154 offset:3072
	ds_read_b128 v[170:173], v155
	ds_read_b128 v[174:177], v155 offset:1024
	ds_read_b128 v[178:181], v155 offset:2048
	ds_read_b128 v[182:185], v155 offset:3072
	s_add_u32 s48, s46, 0xfff00080
	s_addc_u32 s49, s47, -1
	s_cmp_eq_u32 s68, 60
	s_cselect_b32 s51, s39, s49
	s_cselect_b32 s50, s64, s48
	s_cselect_b32 s49, s37, s67
	s_cselect_b32 s48, s65, s66
	v_lshl_add_u64 v[150:151], s[46:47], 0, v[138:139]
	s_add_i32 m0, s45, 0xc000
	ds_read_b128 v[186:189], v156
	ds_read_b128 v[190:193], v156 offset:1024
	ds_read_b128 v[194:197], v156 offset:2048
	ds_read_b128 v[198:201], v156 offset:3072
	ds_read_b128 v[202:205], v156 offset:4096
	ds_read_b128 v[206:209], v156 offset:5120
	ds_read_b128 v[210:213], v156 offset:6144
	ds_read_b128 v[214:217], v156 offset:7168
	global_load_lds_dwordx4 v[150:151], off
	v_lshl_add_u64 v[150:151], s[46:47], 0, v[140:141]
	s_add_i32 m0, s45, 0xe000
	s_nop 0
	global_load_lds_dwordx4 v[150:151], off
	s_waitcnt vmcnt(8)
	s_waitcnt lgkmcnt(0)
	s_barrier
	s_setprio 1
	s_waitcnt lgkmcnt(0)
	v_mfma_f32_16x16x32_bf16 v[126:129], v[146:149], v[186:189], v[126:129]
	v_mfma_f32_16x16x32_bf16 v[122:125], v[162:165], v[186:189], v[122:125]
	v_mfma_f32_16x16x32_bf16 v[118:121], v[146:149], v[194:197], v[118:121]
	v_mfma_f32_16x16x32_bf16 v[114:117], v[162:165], v[194:197], v[114:117]
	v_mfma_f32_16x16x32_bf16 v[102:105], v[146:149], v[202:205], v[102:105]
	v_mfma_f32_16x16x32_bf16 v[98:101], v[162:165], v[202:205], v[98:101]
	v_mfma_f32_16x16x32_bf16 v[86:89], v[146:149], v[210:213], v[86:89]
	v_mfma_f32_16x16x32_bf16 v[78:81], v[162:165], v[210:213], v[78:81]
	v_mfma_f32_16x16x32_bf16 v[126:129], v[158:161], v[190:193], v[126:129]
	v_mfma_f32_16x16x32_bf16 v[122:125], v[166:169], v[190:193], v[122:125]
	v_mfma_f32_16x16x32_bf16 v[118:121], v[158:161], v[198:201], v[118:121]
	v_mfma_f32_16x16x32_bf16 v[114:117], v[166:169], v[198:201], v[114:117]
	v_mfma_f32_16x16x32_bf16 v[102:105], v[158:161], v[206:209], v[102:105]
	v_mfma_f32_16x16x32_bf16 v[98:101], v[166:169], v[206:209], v[98:101]
	v_mfma_f32_16x16x32_bf16 v[86:89], v[158:161], v[214:217], v[86:89]
	v_mfma_f32_16x16x32_bf16 v[78:81], v[166:169], v[214:217], v[78:81]
	s_setprio 0
	s_setprio 1
	v_mfma_f32_16x16x32_bf16 v[110:113], v[170:173], v[186:189], v[110:113]
	v_mfma_f32_16x16x32_bf16 v[106:109], v[178:181], v[186:189], v[106:109]
	v_mfma_f32_16x16x32_bf16 v[94:97], v[170:173], v[194:197], v[94:97]
	v_mfma_f32_16x16x32_bf16 v[90:93], v[178:181], v[194:197], v[90:93]
	v_mfma_f32_16x16x32_bf16 v[82:85], v[170:173], v[202:205], v[82:85]
	v_mfma_f32_16x16x32_bf16 v[74:77], v[178:181], v[202:205], v[74:77]
	v_mfma_f32_16x16x32_bf16 v[70:73], v[170:173], v[210:213], v[70:73]
	v_mfma_f32_16x16x32_bf16 v[66:69], v[178:181], v[210:213], v[66:69]
	v_mfma_f32_16x16x32_bf16 v[110:113], v[174:177], v[190:193], v[110:113]
	v_mfma_f32_16x16x32_bf16 v[106:109], v[182:185], v[190:193], v[106:109]
	s_setprio 3
	s_barrier
	v_mfma_f32_16x16x32_bf16 v[94:97], v[174:177], v[198:201], v[94:97]
	v_mfma_f32_16x16x32_bf16 v[90:93], v[182:185], v[198:201], v[90:93]
	v_mfma_f32_16x16x32_bf16 v[82:85], v[174:177], v[206:209], v[82:85]
	v_mfma_f32_16x16x32_bf16 v[74:77], v[182:185], v[206:209], v[74:77]
	v_mfma_f32_16x16x32_bf16 v[70:73], v[174:177], v[214:217], v[70:73]
	v_mfma_f32_16x16x32_bf16 v[66:69], v[182:185], v[214:217], v[66:69]
	s_setprio 0
	s_add_i32 s69, s61, s53
	v_lshl_add_u64 v[150:151], s[48:49], 0, v[132:133]
	s_mov_b32 m0, s69
	ds_read_b128 v[186:189], v156 offset:16384
	ds_read_b128 v[190:193], v156 offset:17408
	ds_read_b128 v[194:197], v156 offset:18432
	ds_read_b128 v[198:201], v156 offset:19456
	ds_read_b128 v[202:205], v156 offset:20480
	ds_read_b128 v[206:209], v156 offset:21504
	ds_read_b128 v[210:213], v156 offset:22528
	ds_read_b128 v[214:217], v156 offset:23552
	global_load_lds_dwordx4 v[150:151], off
	s_add_i32 m0, s69, 0x2000
	s_add_u32 s70, s48, 0x100000
	v_lshl_add_u64 v[218:219], s[48:49], 0, v[136:137]
	s_addc_u32 s71, s49, 0
	s_add_i32 s69, s62, s53
	global_load_lds_dwordx4 v[218:219], off
	v_lshl_add_u64 v[220:221], s[70:71], 0, v[132:133]
	s_mov_b32 m0, s69
	v_lshl_add_u64 v[222:223], s[50:51], 0, v[134:135]
	global_load_lds_dwordx4 v[220:221], off
	v_lshl_add_u64 v[220:221], s[70:71], 0, v[136:137]
	s_add_i32 m0, s69, 0x2000
	s_nop 0
	global_load_lds_dwordx4 v[220:221], off
	v_lshl_add_u64 v[220:221], s[50:51], 0, v[130:131]
	s_mov_b32 m0, s45
	s_nop 0
	global_load_lds_dwordx4 v[220:221], off
	s_mov_b32 m0, s54
	s_nop 0
	global_load_lds_dwordx4 v[222:223], off
	s_waitcnt vmcnt(8)
	s_waitcnt lgkmcnt(0)
	s_barrier
	s_setprio 1
	s_waitcnt lgkmcnt(0)
	v_mfma_f32_16x16x32_bf16 v[62:65], v[146:149], v[186:189], v[62:65]
	v_mfma_f32_16x16x32_bf16 v[58:61], v[162:165], v[186:189], v[58:61]
	v_mfma_f32_16x16x32_bf16 v[50:53], v[146:149], v[194:197], v[50:53]
	v_mfma_f32_16x16x32_bf16 v[42:45], v[162:165], v[194:197], v[42:45]
	v_mfma_f32_16x16x32_bf16 v[38:41], v[146:149], v[202:205], v[38:41]
	v_mfma_f32_16x16x32_bf16 v[30:33], v[162:165], v[202:205], v[30:33]
	v_mfma_f32_16x16x32_bf16 v[22:25], v[146:149], v[210:213], v[22:25]
	v_mfma_f32_16x16x32_bf16 v[14:17], v[162:165], v[210:213], v[14:17]
	v_mfma_f32_16x16x32_bf16 v[62:65], v[158:161], v[190:193], v[62:65]
	v_mfma_f32_16x16x32_bf16 v[58:61], v[166:169], v[190:193], v[58:61]
	v_mfma_f32_16x16x32_bf16 v[50:53], v[158:161], v[198:201], v[50:53]
	v_mfma_f32_16x16x32_bf16 v[42:45], v[166:169], v[198:201], v[42:45]
	v_mfma_f32_16x16x32_bf16 v[38:41], v[158:161], v[206:209], v[38:41]
	v_mfma_f32_16x16x32_bf16 v[30:33], v[166:169], v[206:209], v[30:33]
	v_mfma_f32_16x16x32_bf16 v[22:25], v[158:161], v[214:217], v[22:25]
	v_mfma_f32_16x16x32_bf16 v[14:17], v[166:169], v[214:217], v[14:17]
	s_setprio 0
	s_setprio 1
	v_mfma_f32_16x16x32_bf16 v[54:57], v[170:173], v[186:189], v[54:57]
	v_mfma_f32_16x16x32_bf16 v[46:49], v[178:181], v[186:189], v[46:49]
	v_mfma_f32_16x16x32_bf16 v[34:37], v[170:173], v[194:197], v[34:37]
	v_mfma_f32_16x16x32_bf16 v[26:29], v[178:181], v[194:197], v[26:29]
	v_mfma_f32_16x16x32_bf16 v[18:21], v[170:173], v[202:205], v[18:21]
	v_mfma_f32_16x16x32_bf16 v[10:13], v[178:181], v[202:205], v[10:13]
	v_mfma_f32_16x16x32_bf16 v[6:9], v[170:173], v[210:213], v[6:9]
	v_mfma_f32_16x16x32_bf16 v[2:5], v[178:181], v[210:213], v[2:5]
	v_mfma_f32_16x16x32_bf16 v[54:57], v[174:177], v[190:193], v[54:57]
	v_mfma_f32_16x16x32_bf16 v[46:49], v[182:185], v[190:193], v[46:49]
	v_mfma_f32_16x16x32_bf16 v[34:37], v[174:177], v[198:201], v[34:37]
	v_mfma_f32_16x16x32_bf16 v[26:29], v[182:185], v[198:201], v[26:29]
	v_mfma_f32_16x16x32_bf16 v[18:21], v[174:177], v[206:209], v[18:21]
	v_mfma_f32_16x16x32_bf16 v[10:13], v[182:185], v[206:209], v[10:13]
	s_setprio 3
	s_barrier
	v_mfma_f32_16x16x32_bf16 v[6:9], v[174:177], v[214:217], v[6:9]
	v_mfma_f32_16x16x32_bf16 v[2:5], v[182:185], v[214:217], v[2:5]
	s_setprio 0
	s_add_i32 s69, 0, 0x18000
	v_add_u32_e32 v157, s69, v152
	s_add_i32 s70, 0, 0x1c000
	ds_read_b128 v[146:149], v157
	ds_read_b128 v[158:161], v157 offset:1024
	ds_read_b128 v[162:165], v157 offset:2048
	ds_read_b128 v[166:169], v157 offset:3072
	v_add_u32_e32 v157, s70, v152
	ds_read_b128 v[170:173], v157
	ds_read_b128 v[174:177], v157 offset:1024
	ds_read_b128 v[178:181], v157 offset:2048
	ds_read_b128 v[182:185], v157 offset:3072
	s_add_u32 s50, s50, 0x100000
	s_addc_u32 s51, s51, 0
	s_mov_b32 m0, s55
	v_lshl_add_u64 v[224:225], s[50:51], 0, v[130:131]
	ds_read_b128 v[186:189], v156 offset:32768
	ds_read_b128 v[190:193], v156 offset:33792
	ds_read_b128 v[194:197], v156 offset:34816
	ds_read_b128 v[198:201], v156 offset:35840
	ds_read_b128 v[202:205], v156 offset:36864
	ds_read_b128 v[206:209], v156 offset:37888
	ds_read_b128 v[210:213], v156 offset:38912
	ds_read_b128 v[214:217], v156 offset:39936
	global_load_lds_dwordx4 v[224:225], off
	v_lshl_add_u64 v[224:225], s[50:51], 0, v[134:135]
	s_mov_b32 m0, s56
	s_nop 0
	global_load_lds_dwordx4 v[224:225], off
	s_waitcnt vmcnt(8)
	s_waitcnt lgkmcnt(0)
	s_barrier
	s_setprio 1
	s_waitcnt lgkmcnt(0)
	v_mfma_f32_16x16x32_bf16 v[126:129], v[146:149], v[186:189], v[126:129]
	v_mfma_f32_16x16x32_bf16 v[122:125], v[162:165], v[186:189], v[122:125]
	v_mfma_f32_16x16x32_bf16 v[118:121], v[146:149], v[194:197], v[118:121]
	v_mfma_f32_16x16x32_bf16 v[114:117], v[162:165], v[194:197], v[114:117]
	v_mfma_f32_16x16x32_bf16 v[102:105], v[146:149], v[202:205], v[102:105]
	v_mfma_f32_16x16x32_bf16 v[98:101], v[162:165], v[202:205], v[98:101]
	v_mfma_f32_16x16x32_bf16 v[86:89], v[146:149], v[210:213], v[86:89]
	v_mfma_f32_16x16x32_bf16 v[78:81], v[162:165], v[210:213], v[78:81]
	v_mfma_f32_16x16x32_bf16 v[126:129], v[158:161], v[190:193], v[126:129]
	v_mfma_f32_16x16x32_bf16 v[122:125], v[166:169], v[190:193], v[122:125]
	v_mfma_f32_16x16x32_bf16 v[118:121], v[158:161], v[198:201], v[118:121]
	v_mfma_f32_16x16x32_bf16 v[114:117], v[166:169], v[198:201], v[114:117]
	v_mfma_f32_16x16x32_bf16 v[102:105], v[158:161], v[206:209], v[102:105]
	v_mfma_f32_16x16x32_bf16 v[98:101], v[166:169], v[206:209], v[98:101]
	v_mfma_f32_16x16x32_bf16 v[86:89], v[158:161], v[214:217], v[86:89]
	v_mfma_f32_16x16x32_bf16 v[78:81], v[166:169], v[214:217], v[78:81]
	s_setprio 0
	s_setprio 1
	v_mfma_f32_16x16x32_bf16 v[110:113], v[170:173], v[186:189], v[110:113]
	v_mfma_f32_16x16x32_bf16 v[106:109], v[178:181], v[186:189], v[106:109]
	v_mfma_f32_16x16x32_bf16 v[94:97], v[170:173], v[194:197], v[94:97]
	v_mfma_f32_16x16x32_bf16 v[90:93], v[178:181], v[194:197], v[90:93]
	v_mfma_f32_16x16x32_bf16 v[82:85], v[170:173], v[202:205], v[82:85]
	v_mfma_f32_16x16x32_bf16 v[74:77], v[178:181], v[202:205], v[74:77]
	v_mfma_f32_16x16x32_bf16 v[70:73], v[170:173], v[210:213], v[70:73]
	v_mfma_f32_16x16x32_bf16 v[66:69], v[178:181], v[210:213], v[66:69]
	v_mfma_f32_16x16x32_bf16 v[110:113], v[174:177], v[190:193], v[110:113]
	v_mfma_f32_16x16x32_bf16 v[106:109], v[182:185], v[190:193], v[106:109]
	s_setprio 3
	s_barrier
	v_mfma_f32_16x16x32_bf16 v[94:97], v[174:177], v[198:201], v[94:97]
	v_mfma_f32_16x16x32_bf16 v[90:93], v[182:185], v[198:201], v[90:93]
	v_mfma_f32_16x16x32_bf16 v[82:85], v[174:177], v[206:209], v[82:85]
	v_mfma_f32_16x16x32_bf16 v[74:77], v[182:185], v[206:209], v[74:77]
	v_mfma_f32_16x16x32_bf16 v[70:73], v[174:177], v[214:217], v[70:73]
	v_mfma_f32_16x16x32_bf16 v[66:69], v[182:185], v[214:217], v[66:69]
	s_setprio 0
	s_add_i32 s50, s69, s53
	v_lshl_add_u64 v[150:151], v[150:151], 0, s[28:29]
	s_mov_b32 m0, s50
	ds_read_b128 v[186:189], v156 offset:49152
	ds_read_b128 v[190:193], v156 offset:50176
	ds_read_b128 v[194:197], v156 offset:51200
	ds_read_b128 v[198:201], v156 offset:52224
	ds_read_b128 v[202:205], v156 offset:53248
	ds_read_b128 v[206:209], v156 offset:54272
	ds_read_b128 v[210:213], v156 offset:55296
	ds_read_b128 v[214:217], v156 offset:56320
	global_load_lds_dwordx4 v[150:151], off
	s_add_i32 m0, s50, 0x2000
	s_add_u32 s48, s48, 0x100080
	v_lshl_add_u64 v[150:151], v[218:219], 0, s[28:29]
	s_addc_u32 s49, s49, 0
	s_add_i32 s50, s70, s53
	global_load_lds_dwordx4 v[150:151], off
	v_lshl_add_u64 v[150:151], s[48:49], 0, v[132:133]
	s_mov_b32 m0, s50
	s_nop 0
	global_load_lds_dwordx4 v[150:151], off
	v_lshl_add_u64 v[150:151], s[48:49], 0, v[136:137]
	s_add_i32 m0, s50, 0x2000
	s_nop 0
	global_load_lds_dwordx4 v[150:151], off
	v_lshl_add_u64 v[150:151], v[220:221], 0, s[28:29]
	s_mov_b32 m0, s58
	s_nop 0
	global_load_lds_dwordx4 v[150:151], off
	v_lshl_add_u64 v[150:151], v[222:223], 0, s[28:29]
	s_mov_b32 m0, s59
	s_nop 0
	global_load_lds_dwordx4 v[150:151], off
	s_waitcnt vmcnt(8)
	s_waitcnt lgkmcnt(0)
	s_barrier
	s_setprio 1
	s_waitcnt lgkmcnt(0)
	v_mfma_f32_16x16x32_bf16 v[62:65], v[146:149], v[186:189], v[62:65]
	v_mfma_f32_16x16x32_bf16 v[58:61], v[162:165], v[186:189], v[58:61]
	v_mfma_f32_16x16x32_bf16 v[50:53], v[146:149], v[194:197], v[50:53]
	v_mfma_f32_16x16x32_bf16 v[42:45], v[162:165], v[194:197], v[42:45]
	v_mfma_f32_16x16x32_bf16 v[38:41], v[146:149], v[202:205], v[38:41]
	v_mfma_f32_16x16x32_bf16 v[30:33], v[162:165], v[202:205], v[30:33]
	v_mfma_f32_16x16x32_bf16 v[22:25], v[146:149], v[210:213], v[22:25]
	v_mfma_f32_16x16x32_bf16 v[14:17], v[162:165], v[210:213], v[14:17]
	v_mfma_f32_16x16x32_bf16 v[62:65], v[158:161], v[190:193], v[62:65]
	v_mfma_f32_16x16x32_bf16 v[58:61], v[166:169], v[190:193], v[58:61]
	v_mfma_f32_16x16x32_bf16 v[50:53], v[158:161], v[198:201], v[50:53]
	v_mfma_f32_16x16x32_bf16 v[42:45], v[166:169], v[198:201], v[42:45]
	v_mfma_f32_16x16x32_bf16 v[38:41], v[158:161], v[206:209], v[38:41]
	v_mfma_f32_16x16x32_bf16 v[30:33], v[166:169], v[206:209], v[30:33]
	v_mfma_f32_16x16x32_bf16 v[22:25], v[158:161], v[214:217], v[22:25]
	v_mfma_f32_16x16x32_bf16 v[14:17], v[166:169], v[214:217], v[14:17]
	s_setprio 0
	s_setprio 1
	v_mfma_f32_16x16x32_bf16 v[54:57], v[170:173], v[186:189], v[54:57]
	v_mfma_f32_16x16x32_bf16 v[46:49], v[178:181], v[186:189], v[46:49]
	v_mfma_f32_16x16x32_bf16 v[34:37], v[170:173], v[194:197], v[34:37]
	v_mfma_f32_16x16x32_bf16 v[26:29], v[178:181], v[194:197], v[26:29]
	v_mfma_f32_16x16x32_bf16 v[18:21], v[170:173], v[202:205], v[18:21]
	v_mfma_f32_16x16x32_bf16 v[10:13], v[178:181], v[202:205], v[10:13]
	v_mfma_f32_16x16x32_bf16 v[6:9], v[170:173], v[210:213], v[6:9]
	v_mfma_f32_16x16x32_bf16 v[2:5], v[178:181], v[210:213], v[2:5]
	v_mfma_f32_16x16x32_bf16 v[54:57], v[174:177], v[190:193], v[54:57]
	v_mfma_f32_16x16x32_bf16 v[46:49], v[182:185], v[190:193], v[46:49]
	v_mfma_f32_16x16x32_bf16 v[34:37], v[174:177], v[198:201], v[34:37]
	v_mfma_f32_16x16x32_bf16 v[26:29], v[182:185], v[198:201], v[26:29]
	v_mfma_f32_16x16x32_bf16 v[18:21], v[174:177], v[206:209], v[18:21]
	v_mfma_f32_16x16x32_bf16 v[10:13], v[182:185], v[206:209], v[10:13]
	s_setprio 3
	s_barrier
	v_mfma_f32_16x16x32_bf16 v[6:9], v[174:177], v[214:217], v[6:9]
	v_mfma_f32_16x16x32_bf16 v[2:5], v[182:185], v[214:217], v[2:5]
	s_setprio 0
	s_add_i32 s68, s68, 2
	s_add_u32 s46, s46, 0x100
	s_addc_u32 s47, s47, 0
	s_add_u32 s66, s66, 0x100
	s_addc_u32 s67, s67, 0
	s_cmp_gt_u32 s68, 61
	s_cbranch_scc0 .LBB0_618
	s_and_b64 vcc, exec, s[30:31]
	s_cbranch_vccz .LBB0_621
	s_barrier

.LBB0_743:
	ds_read_b128 v[130:133], v197
	ds_read_b128 v[134:137], v197 offset:1024
	ds_read_b128 v[138:141], v197 offset:2048
	ds_read_b128 v[142:145], v197 offset:3072
	ds_read_b128 v[146:149], v198
	ds_read_b128 v[150:153], v198 offset:1024
	ds_read_b128 v[154:157], v198 offset:2048
	ds_read_b128 v[158:161], v198 offset:3072
	s_add_u32 s72, s70, 0xfff00080
	s_addc_u32 s73, s71, -1
	s_cmp_eq_u32 s95, 60
	s_cselect_b32 s75, s61, s73
	s_cselect_b32 s74, s67, s72
	s_cselect_b32 s73, s59, s94
	s_cselect_b32 s72, s69, s93
	v_lshl_add_u64 v[184:185], s[70:71], 0, v[176:177]
	s_add_i32 m0, s78, 0xc000
	ds_read_b128 v[200:203], v199
	ds_read_b128 v[204:207], v199 offset:1024
	ds_read_b128 v[208:211], v199 offset:2048
	ds_read_b128 v[212:215], v199 offset:3072
	ds_read_b128 v[216:219], v199 offset:4096
	ds_read_b128 v[220:223], v199 offset:5120
	ds_read_b128 v[224:227], v199 offset:6144
	ds_read_b128 v[228:231], v199 offset:7168
	global_load_lds_dwordx4 v[184:185], off
	v_lshl_add_u64 v[184:185], s[70:71], 0, v[178:179]
	s_add_i32 m0, s78, 0xe000
	s_nop 0
	global_load_lds_dwordx4 v[184:185], off
	s_waitcnt vmcnt(8)
	s_waitcnt lgkmcnt(0)
	s_barrier
	s_setprio 1
	s_waitcnt lgkmcnt(0)
	v_mfma_f32_16x16x32_bf16 v[102:105], v[130:133], v[200:203], v[102:105]
	v_mfma_f32_16x16x32_bf16 v[98:101], v[138:141], v[200:203], v[98:101]
	v_mfma_f32_16x16x32_bf16 v[110:113], v[130:133], v[208:211], v[110:113]
	v_mfma_f32_16x16x32_bf16 v[106:109], v[138:141], v[208:211], v[106:109]
	v_mfma_f32_16x16x32_bf16 v[118:121], v[130:133], v[216:219], v[118:121]
	v_mfma_f32_16x16x32_bf16 v[114:117], v[138:141], v[216:219], v[114:117]
	v_mfma_f32_16x16x32_bf16 v[126:129], v[130:133], v[224:227], v[126:129]
	v_mfma_f32_16x16x32_bf16 v[122:125], v[138:141], v[224:227], v[122:125]
	v_mfma_f32_16x16x32_bf16 v[102:105], v[134:137], v[204:207], v[102:105]
	v_mfma_f32_16x16x32_bf16 v[98:101], v[142:145], v[204:207], v[98:101]
	v_mfma_f32_16x16x32_bf16 v[110:113], v[134:137], v[212:215], v[110:113]
	v_mfma_f32_16x16x32_bf16 v[106:109], v[142:145], v[212:215], v[106:109]
	v_mfma_f32_16x16x32_bf16 v[118:121], v[134:137], v[220:223], v[118:121]
	v_mfma_f32_16x16x32_bf16 v[114:117], v[142:145], v[220:223], v[114:117]
	v_mfma_f32_16x16x32_bf16 v[126:129], v[134:137], v[228:231], v[126:129]
	v_mfma_f32_16x16x32_bf16 v[122:125], v[142:145], v[228:231], v[122:125]
	s_setprio 0
	s_setprio 1
	v_mfma_f32_16x16x32_bf16 v[38:41], v[146:149], v[200:203], v[38:41]
	v_mfma_f32_16x16x32_bf16 v[34:37], v[154:157], v[200:203], v[34:37]
	v_mfma_f32_16x16x32_bf16 v[46:49], v[146:149], v[208:211], v[46:49]
	v_mfma_f32_16x16x32_bf16 v[42:45], v[154:157], v[208:211], v[42:45]
	v_mfma_f32_16x16x32_bf16 v[54:57], v[146:149], v[216:219], v[54:57]
	v_mfma_f32_16x16x32_bf16 v[50:53], v[154:157], v[216:219], v[50:53]
	v_mfma_f32_16x16x32_bf16 v[62:65], v[146:149], v[224:227], v[62:65]
	v_mfma_f32_16x16x32_bf16 v[58:61], v[154:157], v[224:227], v[58:61]
	v_mfma_f32_16x16x32_bf16 v[38:41], v[150:153], v[204:207], v[38:41]
	v_mfma_f32_16x16x32_bf16 v[34:37], v[158:161], v[204:207], v[34:37]
	s_setprio 3
	s_barrier
	v_mfma_f32_16x16x32_bf16 v[46:49], v[150:153], v[212:215], v[46:49]
	v_mfma_f32_16x16x32_bf16 v[42:45], v[158:161], v[212:215], v[42:45]
	v_mfma_f32_16x16x32_bf16 v[54:57], v[150:153], v[220:223], v[54:57]
	v_mfma_f32_16x16x32_bf16 v[50:53], v[158:161], v[220:223], v[50:53]
	v_mfma_f32_16x16x32_bf16 v[62:65], v[150:153], v[228:231], v[62:65]
	v_mfma_f32_16x16x32_bf16 v[58:61], v[158:161], v[228:231], v[58:61]
	s_setprio 0
	s_add_i32 s96, s90, s77
	v_lshl_add_u64 v[184:185], s[72:73], 0, v[164:165]
	s_mov_b32 m0, s96
	ds_read_b128 v[200:203], v199 offset:16384
	ds_read_b128 v[204:207], v199 offset:17408
	ds_read_b128 v[208:211], v199 offset:18432
	ds_read_b128 v[212:215], v199 offset:19456
	ds_read_b128 v[216:219], v199 offset:20480
	ds_read_b128 v[220:223], v199 offset:21504
	ds_read_b128 v[224:227], v199 offset:22528
	ds_read_b128 v[228:231], v199 offset:23552
	global_load_lds_dwordx4 v[184:185], off
	s_add_i32 m0, s96, 0x2000
	s_add_u32 s96, s72, 0x100000
	v_lshl_add_u64 v[232:233], s[72:73], 0, v[168:169]
	s_addc_u32 s97, s73, 0
	s_add_i32 vcc_lo, s91, s77
	global_load_lds_dwordx4 v[232:233], off
	v_lshl_add_u64 v[234:235], s[96:97], 0, v[164:165]
	s_mov_b32 m0, vcc_lo
	v_lshl_add_u64 v[236:237], s[74:75], 0, v[166:167]
	global_load_lds_dwordx4 v[234:235], off
	v_lshl_add_u64 v[234:235], s[96:97], 0, v[168:169]
	s_add_i32 m0, vcc_lo, 0x2000
	s_nop 0
	global_load_lds_dwordx4 v[234:235], off
	v_lshl_add_u64 v[234:235], s[74:75], 0, v[162:163]
	s_mov_b32 m0, s78
	s_nop 0
	global_load_lds_dwordx4 v[234:235], off
	s_mov_b32 m0, s79
	s_nop 0
	global_load_lds_dwordx4 v[236:237], off
	s_waitcnt vmcnt(8)
	s_waitcnt lgkmcnt(0)
	s_barrier
	s_setprio 1
	s_waitcnt lgkmcnt(0)
	v_mfma_f32_16x16x32_bf16 v[70:73], v[130:133], v[200:203], v[70:73]
	v_mfma_f32_16x16x32_bf16 v[66:69], v[138:141], v[200:203], v[66:69]
	v_mfma_f32_16x16x32_bf16 v[78:81], v[130:133], v[208:211], v[78:81]
	v_mfma_f32_16x16x32_bf16 v[74:77], v[138:141], v[208:211], v[74:77]
	v_mfma_f32_16x16x32_bf16 v[86:89], v[130:133], v[216:219], v[86:89]
	v_mfma_f32_16x16x32_bf16 v[82:85], v[138:141], v[216:219], v[82:85]
	v_mfma_f32_16x16x32_bf16 v[94:97], v[130:133], v[224:227], v[94:97]
	v_mfma_f32_16x16x32_bf16 v[90:93], v[138:141], v[224:227], v[90:93]
	v_mfma_f32_16x16x32_bf16 v[70:73], v[134:137], v[204:207], v[70:73]
	v_mfma_f32_16x16x32_bf16 v[66:69], v[142:145], v[204:207], v[66:69]
	v_mfma_f32_16x16x32_bf16 v[78:81], v[134:137], v[212:215], v[78:81]
	v_mfma_f32_16x16x32_bf16 v[74:77], v[142:145], v[212:215], v[74:77]
	v_mfma_f32_16x16x32_bf16 v[86:89], v[134:137], v[220:223], v[86:89]
	v_mfma_f32_16x16x32_bf16 v[82:85], v[142:145], v[220:223], v[82:85]
	v_mfma_f32_16x16x32_bf16 v[94:97], v[134:137], v[228:231], v[94:97]
	v_mfma_f32_16x16x32_bf16 v[90:93], v[142:145], v[228:231], v[90:93]
	s_setprio 0
	s_setprio 1
	v_mfma_f32_16x16x32_bf16 v[6:9], v[146:149], v[200:203], v[6:9]
	v_mfma_f32_16x16x32_bf16 v[2:5], v[154:157], v[200:203], v[2:5]
	v_mfma_f32_16x16x32_bf16 v[14:17], v[146:149], v[208:211], v[14:17]
	v_mfma_f32_16x16x32_bf16 v[10:13], v[154:157], v[208:211], v[10:13]
	v_mfma_f32_16x16x32_bf16 v[22:25], v[146:149], v[216:219], v[22:25]
	v_mfma_f32_16x16x32_bf16 v[18:21], v[154:157], v[216:219], v[18:21]
	v_mfma_f32_16x16x32_bf16 v[30:33], v[146:149], v[224:227], v[30:33]
	v_mfma_f32_16x16x32_bf16 v[26:29], v[154:157], v[224:227], v[26:29]
	v_mfma_f32_16x16x32_bf16 v[6:9], v[150:153], v[204:207], v[6:9]
	v_mfma_f32_16x16x32_bf16 v[2:5], v[158:161], v[204:207], v[2:5]
	v_mfma_f32_16x16x32_bf16 v[14:17], v[150:153], v[212:215], v[14:17]
	v_mfma_f32_16x16x32_bf16 v[10:13], v[158:161], v[212:215], v[10:13]
	v_mfma_f32_16x16x32_bf16 v[22:25], v[150:153], v[220:223], v[22:25]
	v_mfma_f32_16x16x32_bf16 v[18:21], v[158:161], v[220:223], v[18:21]
	s_setprio 3
	s_barrier
	v_mfma_f32_16x16x32_bf16 v[30:33], v[150:153], v[228:231], v[30:33]
	v_mfma_f32_16x16x32_bf16 v[26:29], v[158:161], v[228:231], v[26:29]
	s_setprio 0
	s_add_i32 s96, 0, 0x18000
	s_add_i32 s97, 0, 0x1c000
	v_add_u32_e32 v142, s96, v173
	v_add_u32_e32 v158, s97, v173
	ds_read_b128 v[130:133], v142
	ds_read_b128 v[134:137], v142 offset:1024
	ds_read_b128 v[138:141], v142 offset:2048
	ds_read_b128 v[142:145], v142 offset:3072
	ds_read_b128 v[146:149], v158
	ds_read_b128 v[150:153], v158 offset:1024
	ds_read_b128 v[154:157], v158 offset:2048
	ds_read_b128 v[158:161], v158 offset:3072
	s_add_u32 s74, s74, 0x100000
	s_addc_u32 s75, s75, 0
	s_mov_b32 m0, s80
	v_lshl_add_u64 v[238:239], s[74:75], 0, v[162:163]
	ds_read_b128 v[200:203], v199 offset:32768
	ds_read_b128 v[204:207], v199 offset:33792
	ds_read_b128 v[208:211], v199 offset:34816
	ds_read_b128 v[212:215], v199 offset:35840
	ds_read_b128 v[216:219], v199 offset:36864
	ds_read_b128 v[220:223], v199 offset:37888
	ds_read_b128 v[224:227], v199 offset:38912
	ds_read_b128 v[228:231], v199 offset:39936
	global_load_lds_dwordx4 v[238:239], off
	v_lshl_add_u64 v[238:239], s[74:75], 0, v[166:167]
	s_mov_b32 m0, s81
	s_nop 0
	global_load_lds_dwordx4 v[238:239], off
	s_waitcnt vmcnt(8)
	s_waitcnt lgkmcnt(0)
	s_barrier
	s_setprio 1
	s_waitcnt lgkmcnt(0)
	v_mfma_f32_16x16x32_bf16 v[102:105], v[130:133], v[200:203], v[102:105]
	v_mfma_f32_16x16x32_bf16 v[98:101], v[138:141], v[200:203], v[98:101]
	v_mfma_f32_16x16x32_bf16 v[110:113], v[130:133], v[208:211], v[110:113]
	v_mfma_f32_16x16x32_bf16 v[106:109], v[138:141], v[208:211], v[106:109]
	v_mfma_f32_16x16x32_bf16 v[118:121], v[130:133], v[216:219], v[118:121]
	v_mfma_f32_16x16x32_bf16 v[114:117], v[138:141], v[216:219], v[114:117]
	v_mfma_f32_16x16x32_bf16 v[126:129], v[130:133], v[224:227], v[126:129]
	v_mfma_f32_16x16x32_bf16 v[122:125], v[138:141], v[224:227], v[122:125]
	v_mfma_f32_16x16x32_bf16 v[102:105], v[134:137], v[204:207], v[102:105]
	v_mfma_f32_16x16x32_bf16 v[98:101], v[142:145], v[204:207], v[98:101]
	v_mfma_f32_16x16x32_bf16 v[110:113], v[134:137], v[212:215], v[110:113]
	v_mfma_f32_16x16x32_bf16 v[106:109], v[142:145], v[212:215], v[106:109]
	v_mfma_f32_16x16x32_bf16 v[118:121], v[134:137], v[220:223], v[118:121]
	v_mfma_f32_16x16x32_bf16 v[114:117], v[142:145], v[220:223], v[114:117]
	v_mfma_f32_16x16x32_bf16 v[126:129], v[134:137], v[228:231], v[126:129]
	v_mfma_f32_16x16x32_bf16 v[122:125], v[142:145], v[228:231], v[122:125]
	s_setprio 0
	s_setprio 1
	v_mfma_f32_16x16x32_bf16 v[38:41], v[146:149], v[200:203], v[38:41]
	v_mfma_f32_16x16x32_bf16 v[34:37], v[154:157], v[200:203], v[34:37]
	v_mfma_f32_16x16x32_bf16 v[46:49], v[146:149], v[208:211], v[46:49]
	v_mfma_f32_16x16x32_bf16 v[42:45], v[154:157], v[208:211], v[42:45]
	v_mfma_f32_16x16x32_bf16 v[54:57], v[146:149], v[216:219], v[54:57]
	v_mfma_f32_16x16x32_bf16 v[50:53], v[154:157], v[216:219], v[50:53]
	v_mfma_f32_16x16x32_bf16 v[62:65], v[146:149], v[224:227], v[62:65]
	v_mfma_f32_16x16x32_bf16 v[58:61], v[154:157], v[224:227], v[58:61]
	v_mfma_f32_16x16x32_bf16 v[38:41], v[150:153], v[204:207], v[38:41]
	v_mfma_f32_16x16x32_bf16 v[34:37], v[158:161], v[204:207], v[34:37]
	s_setprio 3
	s_barrier
	v_mfma_f32_16x16x32_bf16 v[46:49], v[150:153], v[212:215], v[46:49]
	v_mfma_f32_16x16x32_bf16 v[42:45], v[158:161], v[212:215], v[42:45]
	v_mfma_f32_16x16x32_bf16 v[54:57], v[150:153], v[220:223], v[54:57]
	v_mfma_f32_16x16x32_bf16 v[50:53], v[158:161], v[220:223], v[50:53]
	v_mfma_f32_16x16x32_bf16 v[62:65], v[150:153], v[228:231], v[62:65]
	v_mfma_f32_16x16x32_bf16 v[58:61], v[158:161], v[228:231], v[58:61]
	s_setprio 0
	s_add_i32 s74, s96, s77
	v_lshl_add_u64 v[184:185], v[184:185], 0, s[38:39]
	s_mov_b32 m0, s74
	ds_read_b128 v[200:203], v199 offset:49152
	ds_read_b128 v[204:207], v199 offset:50176
	ds_read_b128 v[208:211], v199 offset:51200
	ds_read_b128 v[212:215], v199 offset:52224
	ds_read_b128 v[216:219], v199 offset:53248
	ds_read_b128 v[220:223], v199 offset:54272
	ds_read_b128 v[224:227], v199 offset:55296
	ds_read_b128 v[228:231], v199 offset:56320
	global_load_lds_dwordx4 v[184:185], off
	s_add_i32 m0, s74, 0x2000
	s_add_u32 s72, s72, 0x100080
	v_lshl_add_u64 v[184:185], v[232:233], 0, s[38:39]
	s_addc_u32 s73, s73, 0
	s_add_i32 s74, s97, s77
	global_load_lds_dwordx4 v[184:185], off
	v_lshl_add_u64 v[184:185], s[72:73], 0, v[164:165]
	s_mov_b32 m0, s74
	s_nop 0
	global_load_lds_dwordx4 v[184:185], off
	v_lshl_add_u64 v[184:185], s[72:73], 0, v[168:169]
	s_add_i32 m0, s74, 0x2000
	s_nop 0
	global_load_lds_dwordx4 v[184:185], off
	v_lshl_add_u64 v[184:185], v[234:235], 0, s[38:39]
	s_mov_b32 m0, s85
	s_nop 0
	global_load_lds_dwordx4 v[184:185], off
	v_lshl_add_u64 v[184:185], v[236:237], 0, s[38:39]
	s_mov_b32 m0, s86
	s_nop 0
	global_load_lds_dwordx4 v[184:185], off
	s_waitcnt vmcnt(8)
	s_waitcnt lgkmcnt(0)
	s_barrier
	s_setprio 1
	s_waitcnt lgkmcnt(0)
	v_mfma_f32_16x16x32_bf16 v[70:73], v[130:133], v[200:203], v[70:73]
	v_mfma_f32_16x16x32_bf16 v[66:69], v[138:141], v[200:203], v[66:69]
	v_mfma_f32_16x16x32_bf16 v[78:81], v[130:133], v[208:211], v[78:81]
	v_mfma_f32_16x16x32_bf16 v[74:77], v[138:141], v[208:211], v[74:77]
	v_mfma_f32_16x16x32_bf16 v[86:89], v[130:133], v[216:219], v[86:89]
	v_mfma_f32_16x16x32_bf16 v[82:85], v[138:141], v[216:219], v[82:85]
	v_mfma_f32_16x16x32_bf16 v[94:97], v[130:133], v[224:227], v[94:97]
	v_mfma_f32_16x16x32_bf16 v[90:93], v[138:141], v[224:227], v[90:93]
	v_mfma_f32_16x16x32_bf16 v[70:73], v[134:137], v[204:207], v[70:73]
	v_mfma_f32_16x16x32_bf16 v[66:69], v[142:145], v[204:207], v[66:69]
	v_mfma_f32_16x16x32_bf16 v[78:81], v[134:137], v[212:215], v[78:81]
	v_mfma_f32_16x16x32_bf16 v[74:77], v[142:145], v[212:215], v[74:77]
	v_mfma_f32_16x16x32_bf16 v[86:89], v[134:137], v[220:223], v[86:89]
	v_mfma_f32_16x16x32_bf16 v[82:85], v[142:145], v[220:223], v[82:85]
	v_mfma_f32_16x16x32_bf16 v[94:97], v[134:137], v[228:231], v[94:97]
	v_mfma_f32_16x16x32_bf16 v[90:93], v[142:145], v[228:231], v[90:93]
	s_setprio 0
	s_setprio 1
	v_mfma_f32_16x16x32_bf16 v[6:9], v[146:149], v[200:203], v[6:9]
	v_mfma_f32_16x16x32_bf16 v[2:5], v[154:157], v[200:203], v[2:5]
	v_mfma_f32_16x16x32_bf16 v[14:17], v[146:149], v[208:211], v[14:17]
	v_mfma_f32_16x16x32_bf16 v[10:13], v[154:157], v[208:211], v[10:13]
	v_mfma_f32_16x16x32_bf16 v[22:25], v[146:149], v[216:219], v[22:25]
	v_mfma_f32_16x16x32_bf16 v[18:21], v[154:157], v[216:219], v[18:21]
	v_mfma_f32_16x16x32_bf16 v[30:33], v[146:149], v[224:227], v[30:33]
	v_mfma_f32_16x16x32_bf16 v[26:29], v[154:157], v[224:227], v[26:29]
	v_mfma_f32_16x16x32_bf16 v[6:9], v[150:153], v[204:207], v[6:9]
	v_mfma_f32_16x16x32_bf16 v[2:5], v[158:161], v[204:207], v[2:5]
	v_mfma_f32_16x16x32_bf16 v[14:17], v[150:153], v[212:215], v[14:17]
	v_mfma_f32_16x16x32_bf16 v[10:13], v[158:161], v[212:215], v[10:13]
	v_mfma_f32_16x16x32_bf16 v[22:25], v[150:153], v[220:223], v[22:25]
	v_mfma_f32_16x16x32_bf16 v[18:21], v[158:161], v[220:223], v[18:21]
	s_setprio 3
	s_barrier
	v_mfma_f32_16x16x32_bf16 v[30:33], v[150:153], v[228:231], v[30:33]
	v_mfma_f32_16x16x32_bf16 v[26:29], v[158:161], v[228:231], v[26:29]
	s_setprio 0
	s_add_i32 s95, s95, 2
	s_add_u32 s70, s70, 0x100
	s_addc_u32 s71, s71, 0
	s_add_u32 s93, s93, 0x100
	s_addc_u32 s94, s94, 0
	s_cmp_gt_u32 s95, 61
	s_cbranch_scc0 .LBB0_743
	s_and_b64 vcc, exec, s[40:41]
	s_cbranch_vccz .LBB0_746
	s_barrier

.LBB0_902:
	ds_read_b128 v[144:147], v155
	ds_read_b128 v[148:151], v155 offset:1024
	ds_read_b128 v[158:161], v155 offset:2048
	ds_read_b128 v[162:165], v155 offset:3072
	ds_read_b128 v[166:169], v156
	ds_read_b128 v[170:173], v156 offset:1024
	ds_read_b128 v[174:177], v156 offset:2048
	ds_read_b128 v[178:181], v156 offset:3072
	s_add_u32 s50, s48, 0x100
	s_addc_u32 s51, s49, 0
	s_cmpk_eq_i32 s73, 0xa8
	s_cselect_b32 s55, s9, s51
	s_cselect_b32 s54, s8, s50
	s_cselect_b32 s53, s47, s72
	s_cselect_b32 s52, s46, s71
	v_lshl_add_u64 v[214:215], s[48:49], 0, v[136:137]
	s_add_i32 m0, s57, 0xc000
	ds_read_b128 v[182:185], v157
	ds_read_b128 v[186:189], v157 offset:1024
	ds_read_b128 v[190:193], v157 offset:2048
	ds_read_b128 v[194:197], v157 offset:3072
	ds_read_b128 v[198:201], v157 offset:4096
	ds_read_b128 v[202:205], v157 offset:5120
	ds_read_b128 v[206:209], v157 offset:6144
	ds_read_b128 v[210:213], v157 offset:7168
	global_load_lds_dwordx4 v[214:215], off
	v_lshl_add_u64 v[214:215], s[48:49], 0, v[138:139]
	s_add_i32 m0, s57, 0xe000
	s_nop 0
	global_load_lds_dwordx4 v[214:215], off
	s_waitcnt vmcnt(8)
	s_waitcnt lgkmcnt(0)
	s_barrier
	s_setprio 1
	s_waitcnt lgkmcnt(0)
	v_mfma_f32_16x16x32_bf16 v[124:127], v[144:147], v[182:185], v[124:127]
	v_mfma_f32_16x16x32_bf16 v[120:123], v[158:161], v[182:185], v[120:123]
	v_mfma_f32_16x16x32_bf16 v[116:119], v[144:147], v[190:193], v[116:119]
	v_mfma_f32_16x16x32_bf16 v[112:115], v[158:161], v[190:193], v[112:115]
	v_mfma_f32_16x16x32_bf16 v[92:95], v[144:147], v[198:201], v[92:95]
	v_mfma_f32_16x16x32_bf16 v[88:91], v[158:161], v[198:201], v[88:91]
	v_mfma_f32_16x16x32_bf16 v[76:79], v[144:147], v[206:209], v[76:79]
	v_mfma_f32_16x16x32_bf16 v[72:75], v[158:161], v[206:209], v[72:75]
	v_mfma_f32_16x16x32_bf16 v[124:127], v[148:151], v[186:189], v[124:127]
	v_mfma_f32_16x16x32_bf16 v[120:123], v[162:165], v[186:189], v[120:123]
	v_mfma_f32_16x16x32_bf16 v[116:119], v[148:151], v[194:197], v[116:119]
	v_mfma_f32_16x16x32_bf16 v[112:115], v[162:165], v[194:197], v[112:115]
	v_mfma_f32_16x16x32_bf16 v[92:95], v[148:151], v[202:205], v[92:95]
	v_mfma_f32_16x16x32_bf16 v[88:91], v[162:165], v[202:205], v[88:91]
	v_mfma_f32_16x16x32_bf16 v[76:79], v[148:151], v[210:213], v[76:79]
	v_mfma_f32_16x16x32_bf16 v[72:75], v[162:165], v[210:213], v[72:75]
	s_setprio 0
	s_setprio 1
	v_mfma_f32_16x16x32_bf16 v[108:111], v[166:169], v[182:185], v[108:111]
	v_mfma_f32_16x16x32_bf16 v[104:107], v[174:177], v[182:185], v[104:107]
	v_mfma_f32_16x16x32_bf16 v[100:103], v[166:169], v[190:193], v[100:103]
	v_mfma_f32_16x16x32_bf16 v[96:99], v[174:177], v[190:193], v[96:99]
	v_mfma_f32_16x16x32_bf16 v[84:87], v[166:169], v[198:201], v[84:87]
	v_mfma_f32_16x16x32_bf16 v[80:83], v[174:177], v[198:201], v[80:83]
	v_mfma_f32_16x16x32_bf16 v[68:71], v[166:169], v[206:209], v[68:71]
	v_mfma_f32_16x16x32_bf16 v[64:67], v[174:177], v[206:209], v[64:67]
	v_mfma_f32_16x16x32_bf16 v[108:111], v[170:173], v[186:189], v[108:111]
	v_mfma_f32_16x16x32_bf16 v[104:107], v[178:181], v[186:189], v[104:107]
	s_setprio 3
	s_barrier
	v_mfma_f32_16x16x32_bf16 v[100:103], v[170:173], v[194:197], v[100:103]
	v_mfma_f32_16x16x32_bf16 v[96:99], v[178:181], v[194:197], v[96:99]
	v_mfma_f32_16x16x32_bf16 v[84:87], v[170:173], v[202:205], v[84:87]
	v_mfma_f32_16x16x32_bf16 v[80:83], v[178:181], v[202:205], v[80:83]
	v_mfma_f32_16x16x32_bf16 v[68:71], v[170:173], v[210:213], v[68:71]
	v_mfma_f32_16x16x32_bf16 v[64:67], v[178:181], v[210:213], v[64:67]
	s_setprio 0
	s_add_i32 s48, s65, s56
	v_lshl_add_u64 v[214:215], s[52:53], 0, v[130:131]
	s_mov_b32 m0, s48
	ds_read_b128 v[182:185], v157 offset:16384
	ds_read_b128 v[186:189], v157 offset:17408
	ds_read_b128 v[190:193], v157 offset:18432
	ds_read_b128 v[194:197], v157 offset:19456
	ds_read_b128 v[198:201], v157 offset:20480
	ds_read_b128 v[202:205], v157 offset:21504
	ds_read_b128 v[206:209], v157 offset:22528
	ds_read_b128 v[210:213], v157 offset:23552
	global_load_lds_dwordx4 v[214:215], off
	s_add_i32 m0, s48, 0x2000
	s_add_u32 s48, s52, 0x2b0000
	v_lshl_add_u64 v[216:217], s[52:53], 0, v[134:135]
	s_addc_u32 s49, s53, 0
	s_add_i32 s74, s66, s56
	global_load_lds_dwordx4 v[216:217], off
	v_lshl_add_u64 v[218:219], s[48:49], 0, v[130:131]
	s_mov_b32 m0, s74
	v_lshl_add_u64 v[220:221], s[54:55], 0, v[132:133]
	global_load_lds_dwordx4 v[218:219], off
	v_lshl_add_u64 v[218:219], s[48:49], 0, v[134:135]
	s_add_i32 m0, s74, 0x2000
	s_nop 0
	global_load_lds_dwordx4 v[218:219], off
	v_lshl_add_u64 v[218:219], s[54:55], 0, v[128:129]
	s_mov_b32 m0, s57
	s_nop 0
	global_load_lds_dwordx4 v[218:219], off
	s_mov_b32 m0, s58
	s_nop 0
	global_load_lds_dwordx4 v[220:221], off
	s_waitcnt vmcnt(8)
	s_waitcnt lgkmcnt(0)
	s_barrier
	s_setprio 1
	s_waitcnt lgkmcnt(0)
	v_mfma_f32_16x16x32_bf16 v[60:63], v[144:147], v[182:185], v[60:63]
	v_mfma_f32_16x16x32_bf16 v[56:59], v[158:161], v[182:185], v[56:59]
	v_mfma_f32_16x16x32_bf16 v[44:47], v[144:147], v[190:193], v[44:47]
	v_mfma_f32_16x16x32_bf16 v[40:43], v[158:161], v[190:193], v[40:43]
	v_mfma_f32_16x16x32_bf16 v[28:31], v[144:147], v[198:201], v[28:31]
	v_mfma_f32_16x16x32_bf16 v[24:27], v[158:161], v[198:201], v[24:27]
	v_mfma_f32_16x16x32_bf16 v[12:15], v[144:147], v[206:209], v[12:15]
	v_mfma_f32_16x16x32_bf16 v[8:11], v[158:161], v[206:209], v[8:11]
	v_mfma_f32_16x16x32_bf16 v[60:63], v[148:151], v[186:189], v[60:63]
	v_mfma_f32_16x16x32_bf16 v[56:59], v[162:165], v[186:189], v[56:59]
	v_mfma_f32_16x16x32_bf16 v[44:47], v[148:151], v[194:197], v[44:47]
	v_mfma_f32_16x16x32_bf16 v[40:43], v[162:165], v[194:197], v[40:43]
	v_mfma_f32_16x16x32_bf16 v[28:31], v[148:151], v[202:205], v[28:31]
	v_mfma_f32_16x16x32_bf16 v[24:27], v[162:165], v[202:205], v[24:27]
	v_mfma_f32_16x16x32_bf16 v[12:15], v[148:151], v[210:213], v[12:15]
	v_mfma_f32_16x16x32_bf16 v[8:11], v[162:165], v[210:213], v[8:11]
	s_setprio 0
	s_setprio 1
	v_mfma_f32_16x16x32_bf16 v[52:55], v[166:169], v[182:185], v[52:55]
	v_mfma_f32_16x16x32_bf16 v[48:51], v[174:177], v[182:185], v[48:51]
	v_mfma_f32_16x16x32_bf16 v[36:39], v[166:169], v[190:193], v[36:39]
	v_mfma_f32_16x16x32_bf16 v[32:35], v[174:177], v[190:193], v[32:35]
	v_mfma_f32_16x16x32_bf16 v[20:23], v[166:169], v[198:201], v[20:23]
	v_mfma_f32_16x16x32_bf16 v[16:19], v[174:177], v[198:201], v[16:19]
	v_mfma_f32_16x16x32_bf16 v[4:7], v[166:169], v[206:209], v[4:7]
	v_mfma_f32_16x16x32_bf16 v[0:3], v[174:177], v[206:209], v[0:3]
	v_mfma_f32_16x16x32_bf16 v[52:55], v[170:173], v[186:189], v[52:55]
	v_mfma_f32_16x16x32_bf16 v[48:51], v[178:181], v[186:189], v[48:51]
	v_mfma_f32_16x16x32_bf16 v[36:39], v[170:173], v[194:197], v[36:39]
	v_mfma_f32_16x16x32_bf16 v[32:35], v[178:181], v[194:197], v[32:35]
	v_mfma_f32_16x16x32_bf16 v[20:23], v[170:173], v[202:205], v[20:23]
	v_mfma_f32_16x16x32_bf16 v[16:19], v[178:181], v[202:205], v[16:19]
	s_setprio 3
	s_barrier
	v_mfma_f32_16x16x32_bf16 v[4:7], v[170:173], v[210:213], v[4:7]
	v_mfma_f32_16x16x32_bf16 v[0:3], v[178:181], v[210:213], v[0:3]
	s_setprio 0
	s_add_i32 s74, 0, 0x18000
	s_add_i32 s75, 0, 0x1c000
	v_add_u32_e32 v162, s74, v153
	v_add_u32_e32 v178, s75, v153
	ds_read_b128 v[144:147], v162
	ds_read_b128 v[148:151], v162 offset:1024
	ds_read_b128 v[158:161], v162 offset:2048
	ds_read_b128 v[162:165], v162 offset:3072
	ds_read_b128 v[166:169], v178
	ds_read_b128 v[170:173], v178 offset:1024
	ds_read_b128 v[174:177], v178 offset:2048
	ds_read_b128 v[178:181], v178 offset:3072
	s_add_u32 s48, s54, 0x2b0000
	s_addc_u32 s49, s55, 0
	s_mov_b32 m0, s59
	v_lshl_add_u64 v[222:223], s[48:49], 0, v[128:129]
	ds_read_b128 v[182:185], v157 offset:32768
	ds_read_b128 v[186:189], v157 offset:33792
	ds_read_b128 v[190:193], v157 offset:34816
	ds_read_b128 v[194:197], v157 offset:35840
	ds_read_b128 v[198:201], v157 offset:36864
	ds_read_b128 v[202:205], v157 offset:37888
	ds_read_b128 v[206:209], v157 offset:38912
	ds_read_b128 v[210:213], v157 offset:39936
	global_load_lds_dwordx4 v[222:223], off
	v_lshl_add_u64 v[222:223], s[48:49], 0, v[132:133]
	s_mov_b32 m0, s60
	s_nop 0
	global_load_lds_dwordx4 v[222:223], off
	s_waitcnt vmcnt(8)
	s_waitcnt lgkmcnt(0)
	s_barrier
	s_setprio 1
	s_waitcnt lgkmcnt(0)
	v_mfma_f32_16x16x32_bf16 v[124:127], v[144:147], v[182:185], v[124:127]
	v_mfma_f32_16x16x32_bf16 v[120:123], v[158:161], v[182:185], v[120:123]
	v_mfma_f32_16x16x32_bf16 v[116:119], v[144:147], v[190:193], v[116:119]
	v_mfma_f32_16x16x32_bf16 v[112:115], v[158:161], v[190:193], v[112:115]
	v_mfma_f32_16x16x32_bf16 v[92:95], v[144:147], v[198:201], v[92:95]
	v_mfma_f32_16x16x32_bf16 v[88:91], v[158:161], v[198:201], v[88:91]
	v_mfma_f32_16x16x32_bf16 v[76:79], v[144:147], v[206:209], v[76:79]
	v_mfma_f32_16x16x32_bf16 v[72:75], v[158:161], v[206:209], v[72:75]
	v_mfma_f32_16x16x32_bf16 v[124:127], v[148:151], v[186:189], v[124:127]
	v_mfma_f32_16x16x32_bf16 v[120:123], v[162:165], v[186:189], v[120:123]
	v_mfma_f32_16x16x32_bf16 v[116:119], v[148:151], v[194:197], v[116:119]
	v_mfma_f32_16x16x32_bf16 v[112:115], v[162:165], v[194:197], v[112:115]
	v_mfma_f32_16x16x32_bf16 v[92:95], v[148:151], v[202:205], v[92:95]
	v_mfma_f32_16x16x32_bf16 v[88:91], v[162:165], v[202:205], v[88:91]
	v_mfma_f32_16x16x32_bf16 v[76:79], v[148:151], v[210:213], v[76:79]
	v_mfma_f32_16x16x32_bf16 v[72:75], v[162:165], v[210:213], v[72:75]
	s_setprio 0
	s_setprio 1
	v_mfma_f32_16x16x32_bf16 v[108:111], v[166:169], v[182:185], v[108:111]
	v_mfma_f32_16x16x32_bf16 v[104:107], v[174:177], v[182:185], v[104:107]
	v_mfma_f32_16x16x32_bf16 v[100:103], v[166:169], v[190:193], v[100:103]
	v_mfma_f32_16x16x32_bf16 v[96:99], v[174:177], v[190:193], v[96:99]
	v_mfma_f32_16x16x32_bf16 v[84:87], v[166:169], v[198:201], v[84:87]
	v_mfma_f32_16x16x32_bf16 v[80:83], v[174:177], v[198:201], v[80:83]
	v_mfma_f32_16x16x32_bf16 v[68:71], v[166:169], v[206:209], v[68:71]
	v_mfma_f32_16x16x32_bf16 v[64:67], v[174:177], v[206:209], v[64:67]
	v_mfma_f32_16x16x32_bf16 v[108:111], v[170:173], v[186:189], v[108:111]
	v_mfma_f32_16x16x32_bf16 v[104:107], v[178:181], v[186:189], v[104:107]
	s_setprio 3
	s_barrier
	v_mfma_f32_16x16x32_bf16 v[100:103], v[170:173], v[194:197], v[100:103]
	v_mfma_f32_16x16x32_bf16 v[96:99], v[178:181], v[194:197], v[96:99]
	v_mfma_f32_16x16x32_bf16 v[84:87], v[170:173], v[202:205], v[84:87]
	v_mfma_f32_16x16x32_bf16 v[80:83], v[178:181], v[202:205], v[80:83]
	v_mfma_f32_16x16x32_bf16 v[68:71], v[170:173], v[210:213], v[68:71]
	v_mfma_f32_16x16x32_bf16 v[64:67], v[178:181], v[210:213], v[64:67]
	s_setprio 0
	s_add_i32 s48, s74, s56
	v_lshl_add_u64 v[214:215], v[214:215], 0, s[30:31]
	s_mov_b32 m0, s48
	ds_read_b128 v[182:185], v157 offset:49152
	ds_read_b128 v[186:189], v157 offset:50176
	ds_read_b128 v[190:193], v157 offset:51200
	ds_read_b128 v[194:197], v157 offset:52224
	ds_read_b128 v[198:201], v157 offset:53248
	ds_read_b128 v[202:205], v157 offset:54272
	ds_read_b128 v[206:209], v157 offset:55296
	ds_read_b128 v[210:213], v157 offset:56320
	global_load_lds_dwordx4 v[214:215], off
	s_add_i32 m0, s48, 0x2000
	s_add_u32 s48, s52, 0x2b0080
	v_lshl_add_u64 v[214:215], v[216:217], 0, s[30:31]
	s_addc_u32 s49, s53, 0
	s_add_i32 s52, s75, s56
	global_load_lds_dwordx4 v[214:215], off
	v_lshl_add_u64 v[214:215], s[48:49], 0, v[130:131]
	s_mov_b32 m0, s52
	s_nop 0
	global_load_lds_dwordx4 v[214:215], off
	v_lshl_add_u64 v[214:215], s[48:49], 0, v[134:135]
	s_add_i32 m0, s52, 0x2000
	s_nop 0
	global_load_lds_dwordx4 v[214:215], off
	v_lshl_add_u64 v[214:215], v[218:219], 0, s[30:31]
	s_mov_b32 m0, s62
	s_nop 0
	global_load_lds_dwordx4 v[214:215], off
	v_lshl_add_u64 v[214:215], v[220:221], 0, s[30:31]
	s_mov_b32 m0, s63
	s_nop 0
	global_load_lds_dwordx4 v[214:215], off
	s_waitcnt vmcnt(8)
	s_waitcnt lgkmcnt(0)
	s_barrier
	s_setprio 1
	s_waitcnt lgkmcnt(0)
	v_mfma_f32_16x16x32_bf16 v[60:63], v[144:147], v[182:185], v[60:63]
	v_mfma_f32_16x16x32_bf16 v[56:59], v[158:161], v[182:185], v[56:59]
	v_mfma_f32_16x16x32_bf16 v[44:47], v[144:147], v[190:193], v[44:47]
	v_mfma_f32_16x16x32_bf16 v[40:43], v[158:161], v[190:193], v[40:43]
	v_mfma_f32_16x16x32_bf16 v[28:31], v[144:147], v[198:201], v[28:31]
	v_mfma_f32_16x16x32_bf16 v[24:27], v[158:161], v[198:201], v[24:27]
	v_mfma_f32_16x16x32_bf16 v[12:15], v[144:147], v[206:209], v[12:15]
	v_mfma_f32_16x16x32_bf16 v[8:11], v[158:161], v[206:209], v[8:11]
	v_mfma_f32_16x16x32_bf16 v[60:63], v[148:151], v[186:189], v[60:63]
	v_mfma_f32_16x16x32_bf16 v[56:59], v[162:165], v[186:189], v[56:59]
	v_mfma_f32_16x16x32_bf16 v[44:47], v[148:151], v[194:197], v[44:47]
	v_mfma_f32_16x16x32_bf16 v[40:43], v[162:165], v[194:197], v[40:43]
	v_mfma_f32_16x16x32_bf16 v[28:31], v[148:151], v[202:205], v[28:31]
	v_mfma_f32_16x16x32_bf16 v[24:27], v[162:165], v[202:205], v[24:27]
	v_mfma_f32_16x16x32_bf16 v[12:15], v[148:151], v[210:213], v[12:15]
	v_mfma_f32_16x16x32_bf16 v[8:11], v[162:165], v[210:213], v[8:11]
	s_setprio 0
	s_setprio 1
	v_mfma_f32_16x16x32_bf16 v[52:55], v[166:169], v[182:185], v[52:55]
	v_mfma_f32_16x16x32_bf16 v[48:51], v[174:177], v[182:185], v[48:51]
	v_mfma_f32_16x16x32_bf16 v[36:39], v[166:169], v[190:193], v[36:39]
	v_mfma_f32_16x16x32_bf16 v[32:35], v[174:177], v[190:193], v[32:35]
	v_mfma_f32_16x16x32_bf16 v[20:23], v[166:169], v[198:201], v[20:23]
	v_mfma_f32_16x16x32_bf16 v[16:19], v[174:177], v[198:201], v[16:19]
	v_mfma_f32_16x16x32_bf16 v[4:7], v[166:169], v[206:209], v[4:7]
	v_mfma_f32_16x16x32_bf16 v[0:3], v[174:177], v[206:209], v[0:3]
	v_mfma_f32_16x16x32_bf16 v[52:55], v[170:173], v[186:189], v[52:55]
	v_mfma_f32_16x16x32_bf16 v[48:51], v[178:181], v[186:189], v[48:51]
	v_mfma_f32_16x16x32_bf16 v[36:39], v[170:173], v[194:197], v[36:39]
	v_mfma_f32_16x16x32_bf16 v[32:35], v[178:181], v[194:197], v[32:35]
	v_mfma_f32_16x16x32_bf16 v[20:23], v[170:173], v[202:205], v[20:23]
	v_mfma_f32_16x16x32_bf16 v[16:19], v[178:181], v[202:205], v[16:19]
	s_setprio 3
	s_barrier
	v_mfma_f32_16x16x32_bf16 v[4:7], v[170:173], v[210:213], v[4:7]
	v_mfma_f32_16x16x32_bf16 v[0:3], v[178:181], v[210:213], v[0:3]
	s_setprio 0
	s_add_i32 s73, s73, 2
	s_add_u32 s71, s71, 0x100
	s_addc_u32 s72, s72, 0
	s_cmpk_gt_u32 s73, 0xa9
	s_mov_b64 s[48:49], s[50:51]
	s_cbranch_scc0 .LBB0_902
	s_and_b64 vcc, exec, s[34:35]
	s_cbranch_vccz .LBB0_905
	s_barrier
